# v073 + next tile's scalars, pointer advances, DMA and K-read addresses prepared inside the PV/exp block (off the barrier-to-QK path)
# speedup vs baseline: 1.0122x; 1.0043x over previous
; __device__ __forceinline__ int pi32(int r) { return (r & ~12) | ((r & 4) << 1) | ((r & 8) >> 1); }
; #define AT_DMA(tr) do { const unsigned sb_ = (unsigned)__builtin_amdgcn_readfirstlane(dk + (((tr) & (NSTG - 1)) * STAGE)); const size_t ko_ = (size_t)(tr) * 26 * 4096, vo_ = (size_t)(tr) * 640 * 64; \
;         glds16(kg + ko_, sb_ + OFF_K0); if (!WIN) glds16(kg + ko_ + 4096, sb_ + OFF_K1); glds16(vg + vo_, sb_ + OFF_V); if (!WIN) glds16(vg + vo_ + 64 * 64, sb_ + OFF_V + 8192); } while (0)
; template <bool WIN> ...
;     ...
;     const bf16_t* kg = QK + ((size_t)((seq_base >> 6) + t_lo) * 26 * 64 + drow) * 64 + dch * 8 + kcol0 * 64;
;     const bf16_t* vg = VT + ((size_t)((seq_base >> 6) + t_lo) * 640 + vrow0 + drow) * 64 + dch * 8;
;     const unsigned dk = ldsb + wid * 1024;
;     ...
;     constexpr int NPW = WIN ? 2 : 4;
;     bf16x8 qfr[4];
;     { const int qrow = seq_base + qw + l31; const bf16_t* qp = QK + ((size_t)((qrow >> 6) * 26 + (qcol >> 6)) * 64 + (qrow & 63)) * 64 + hi * 8;
; #pragma unroll
;       for (int ds = 0; ds < 4; ++ds) qfr[ds] = *(const bf16x8*)(qp + ds * 16); }
;     ...
;     AT_DMA(0); if (NT > 1) AT_DMA(1); if (NT > 2) AT_DMA(2);
;     constexpr float THR = 8.0f;
;     float m_ref = WIN ? sinkp[2 * hsel + half] * LOG2E : 0.f;
;     float l_run = (WIN && hi == 0) ? 1.f : 0.f;
;     float cbase = 0.f;
;     f32x16 cvec;
; #pragma unroll
;     for (int r = 0; r < 16; ++r) cvec[r] = cbase - m_ref;
;     f32x16 o[NDB];
; #pragma unroll
;     for (int db = 0; db < NDB; ++db)
; #pragma unroll
;         for (int r = 0; r < 16; ++r) o[db][r] = 0.f;
;     const int krow = pi32(l31), fK = (krow >> 1) & 7, fV = (l31 >> 1) & 7;
;     int kx[4], vx[4];
; #pragma unroll
;     for (int c = 0; c < 4; ++c) { kx[c] = (WIN ? OFF_K0 : (half ? OFF_K1 : OFF_K0)) + krow * 128 + (((2 * c + hi) ^ fK) << 4); vx[c] = OFF_V + l31 * 128 + (((2 * c + hi) ^ fV) << 4); }
;     const int qabs = qw + l31;
;     const float cfar_lo = __uint_as_float(__builtin_amdgcn_readfirstlane(__float_as_uint(lut[0]))), cfar_hi = __uint_as_float(__builtin_amdgcn_readfirstlane(__float_as_uint(lut[LUTW - 1])));
.LBB0_244:
	s_lshl_b32 s62, s33, 5
	s_lshl_b32 s20, s33, 2
	s_and_b32 s62, s62, 32
	v_readfirstlane_b32 s64, v230
	s_and_b32 s20, s20, 24
	s_add_i32 s62, s62, s22
	s_bfe_u32 s77, s64, 0x20006
	s_or_b32 s20, s20, s24
	s_lshl_b32 s62, s62, 7
	s_lshl_b32 s82, s77, 5
	s_lshl_b32 s20, s20, 11
	s_or_b32 s78, s82, s62
	s_and_b32 s20, s20, 0xe000
	s_lshr_b32 s76, s64, 8
	v_or_b32_e32 v4, s78, v185
	v_add_u32_e32 v170, s20, v4
	s_add_i32 s62, s76, s66
	v_ashrrev_i32_e32 v2, 6, v170
	v_mov_b32_e32 v0, s62
	v_mad_u64_u32 v[2:3], s[62:63], v2, 26, v[0:1]
	v_ashrrev_i32_e32 v3, 31, v2
	v_lshlrev_b64 v[2:3], 13, v[2:3]
	v_lshlrev_b32_e32 v0, 7, v4
	v_lshl_add_u64 v[2:3], s[6:7], 0, v[2:3]
	v_and_b32_e32 v4, 0x1f80, v0
	v_mov_b32_e32 v5, v1
	v_lshl_add_u64 v[2:3], v[2:3], 0, v[4:5]
	v_lshl_add_u64 v[2:3], v[2:3], 0, v[164:165]
	global_load_dwordx4 v[114:117], v[2:3], off offset:96
	global_load_dwordx4 v[118:121], v[2:3], off offset:64
	global_load_dwordx4 v[122:125], v[2:3], off offset:32
	global_load_dwordx4 v[126:129], v[2:3], off
	s_lshl_b32 s62, s31, 11
	s_and_b32 s62, s62, 0xffffc000
	s_or_b32 s62, s26, s62
	v_cndmask_b32_e64 v0, 0, 1, s[38:39]
	s_lshr_b32 s81, s62, 13
	v_readfirstlane_b32 s62, v0
	s_lshr_b32 s63, s64, 4
	s_lshl_b32 s83, s62, 12
	s_lshr_b32 s62, s64, 6
	s_and_b32 s63, s63, 4
	s_lshl_b32 s84, s62, 3
	v_bitop3_b32 v4, s63, v186, v189 bitop3:0x36
	s_lshr_b32 s63, s20, 6
	v_or_b32_e32 v0, s84, v188
	s_mul_i32 s20, s63, 0x680
	v_lshl_add_u64 v[2:3], s[20:21], 0, v[0:1]
	v_lshlrev_b64 v[2:3], 7, v[2:3]
	v_lshl_add_u64 v[2:3], s[6:7], 0, v[2:3]
	v_lshlrev_b32_e32 v4, 4, v4
	v_lshl_add_u64 v[2:3], v[2:3], 0, v[4:5]
	s_mul_i32 s20, s63, 0x280
	v_add_u32_e32 v6, s12, v0
	v_mov_b32_e32 v7, v1
	v_lshl_add_u64 v[2:3], v[2:3], 0, s[18:19]
	v_lshl_add_u64 v[6:7], v[6:7], 0, s[20:21]
	s_lshl_b32 s20, s62, 10
	s_mov_b64 s[62:63], 0x24000
	v_lshl_add_u64 v[8:9], v[2:3], 0, s[62:63]
	s_add_i32 s20, s20, 0
	s_mov_b32 s62, m0
	s_mov_b32 m0, s20
	s_nop 0
	global_load_lds_dwordx4 v[8:9], off
	s_mov_b32 m0, s62
	s_mov_b64 s[62:63], 0x26000
	v_lshlrev_b64 v[6:7], 7, v[6:7]
	v_lshl_add_u64 v[8:9], v[2:3], 0, s[62:63]
	s_add_i32 s62, s20, 0x2000
	v_lshl_add_u64 v[6:7], s[4:5], 0, v[6:7]
	s_mov_b32 s63, m0
	s_mov_b32 m0, s62
	s_nop 0
	global_load_lds_dwordx4 v[8:9], off
	s_mov_b32 m0, s63
	s_add_i32 s62, s20, 0x4000
	v_lshl_add_u64 v[6:7], v[6:7], 0, v[4:5]
	s_mov_b32 s63, m0
	s_mov_b32 m0, s62
	s_nop 0
	global_load_lds_dwordx4 v[6:7], off
	s_mov_b32 m0, s63
	s_add_i32 s62, s20, 0x6000
	v_lshl_add_u64 v[8:9], v[6:7], 0, s[40:41]
	s_mov_b32 s63, m0
	s_mov_b32 m0, s62
	s_nop 0
	global_load_lds_dwordx4 v[8:9], off
	s_mov_b32 m0, s63
	s_add_i32 s62, s20, 0x8000
	v_lshl_add_u64 v[8:9], v[2:3], 0, s[42:43]
	s_mov_b32 s63, m0
	s_mov_b32 m0, s62
	s_nop 0
	global_load_lds_dwordx4 v[8:9], off
	s_mov_b32 m0, s63
	s_add_i32 s62, s20, 0xa000
	v_lshl_add_u64 v[8:9], v[2:3], 0, s[46:47]
	s_mov_b32 s63, m0
	s_mov_b32 m0, s62
	s_nop 0
	global_load_lds_dwordx4 v[8:9], off
	s_mov_b32 m0, s63
	s_add_i32 s62, s20, 0xc000
	v_lshl_add_u64 v[8:9], v[6:7], 0, s[48:49]
	s_mov_b32 s63, m0
	s_mov_b32 m0, s62
	s_nop 0
	global_load_lds_dwordx4 v[8:9], off
	s_mov_b32 m0, s63
	s_add_i32 s62, s20, 0xe000
	v_lshl_add_u64 v[8:9], v[6:7], 0, s[50:51]
	s_mov_b32 s63, m0
	s_mov_b32 m0, s62
	s_nop 0
	global_load_lds_dwordx4 v[8:9], off
	s_mov_b32 m0, s63
	s_add_i32 s62, s20, 0x10000
	v_lshl_add_u64 v[8:9], v[2:3], 0, s[52:53]
	s_mov_b32 s63, m0
	s_mov_b32 m0, s62
	s_nop 0
	global_load_lds_dwordx4 v[8:9], off
	s_mov_b32 m0, s63
	s_add_i32 s62, s20, 0x12000
	v_lshl_add_u64 v[2:3], v[2:3], 0, s[54:55]
	s_mov_b32 s63, m0
	s_mov_b32 m0, s62
	s_nop 0
	global_load_lds_dwordx4 v[2:3], off
	s_mov_b32 m0, s63
	s_add_i32 s62, s20, 0x14000
	v_lshl_add_u64 v[2:3], v[6:7], 0, s[56:57]
	s_add_i32 s62, s20, 0x16000
	v_lshl_add_u64 v[2:3], v[6:7], 0, s[58:59]
	s_cmpk_lt_u32 s64, 0x100
	s_cselect_b64 s[62:63], -1, 0
	s_and_b64 s[64:65], s[62:63], exec
	s_cselect_b32 s64, 0, 0x2000
	s_add_i32 s67, s27, 0x20000
	v_mov_b32_e32 v2, s67
	ds_read_b32 v3, v2 offset:14336
	ds_read_b32 v2, v2 offset:16124
	v_or_b32_e32 v162, s64, v177
	v_mov_b32_e32 v14, v1
	v_mov_b32_e32 v15, v1
	s_waitcnt lgkmcnt(1)
; __device__ __forceinline__ int pi32(int r) { return (r & ~12) | ((r & 4) << 1) | ((r & 8) >> 1); }
; template <bool WIN> ...
;     ...
;     float m_ref = WIN ? sinkp[2 * hsel + half] * LOG2E : 0.f;
;     float l_run = (WIN && hi == 0) ? 1.f : 0.f;
;     float cbase = 0.f;
;     f32x16 cvec;
; #pragma unroll
;     for (int r = 0; r < 16; ++r) cvec[r] = cbase - m_ref;
;     f32x16 o[NDB];
; #pragma unroll
;     for (int db = 0; db < NDB; ++db)
; #pragma unroll
;         for (int r = 0; r < 16; ++r) o[db][r] = 0.f;
;     const int krow = pi32(l31), fK = (krow >> 1) & 7, fV = (l31 >> 1) & 7;
;     int kx[4], vx[4];
; #pragma unroll
;     for (int c = 0; c < 4; ++c) { kx[c] = (WIN ? OFF_K0 : (half ? OFF_K1 : OFF_K0)) + krow * 128 + (((2 * c + hi) ^ fK) << 4); vx[c] = OFF_V + l31 * 128 + (((2 * c + hi) ^ fV) << 4); }
;     const int qabs = qw + l31;
;     const float cfar_lo = __uint_as_float(__builtin_amdgcn_readfirstlane(__float_as_uint(lut[0]))), cfar_hi = __uint_as_float(__builtin_amdgcn_readfirstlane(__float_as_uint(lut[LUTW - 1])));
;     asm volatile("" : "+v"(qfr[0]), "+v"(qfr[1]), "+v"(qfr[2]), "+v"(qfr[3]));
	v_readfirstlane_b32 s79, v3
	s_waitcnt lgkmcnt(0)
	v_readfirstlane_b32 s80, v2
	v_add_u32_e32 v2, s84, v197
	v_mov_b32_e32 v3, v1
	v_lshlrev_b64 v[2:3], 7, v[2:3]
	v_mad_u64_u32 v[2:3], s[64:65], s81, v199, v[2:3]
	v_or_b32_e32 v2, v2, v4
	v_lshl_add_u64 v[172:173], s[36:37], 0, v[2:3]
	v_lshlrev_b64 v[2:3], 7, v[0:1]
	v_mad_u64_u32 v[2:3], s[64:65], s81, v200, v[2:3]
	s_or_b32 s64, s82, s83
	v_or_b32_e32 v2, v2, v4
	v_add_lshl_u32 v0, s64, v198, 2
	v_lshl_add_u64 v[174:175], s[16:17], 0, v[2:3]
	v_sub_u32_e32 v171, v195, v0
	s_sub_i32 s64, s28, s82
	v_mov_b32_e32 v0, v1
	v_mov_b32_e32 v2, v1
	v_mov_b32_e32 v3, v1
	v_mov_b32_e32 v4, v1
	v_mov_b32_e32 v6, v1
	v_mov_b32_e32 v7, v1
	v_mov_b32_e32 v8, v1
	v_mov_b32_e32 v9, v1
	v_mov_b32_e32 v10, v1
	v_mov_b32_e32 v11, v1
	v_mov_b32_e32 v12, v1
	v_mov_b32_e32 v13, v1
	v_mov_b64_e32 v[64:65], v[14:15]
	v_mov_b64_e32 v[48:49], v[14:15]
	v_mov_b64_e32 v[32:33], v[14:15]
	s_sub_i32 s81, s64, s83
	s_add_i32 s64, s29, s83
	v_mov_b64_e32 v[62:63], v[12:13]
	v_mov_b64_e32 v[60:61], v[10:11]
	v_mov_b64_e32 v[58:59], v[8:9]
	v_mov_b64_e32 v[56:57], v[6:7]
	v_mov_b64_e32 v[54:55], v[4:5]
	v_mov_b64_e32 v[52:53], v[2:3]
	v_mov_b64_e32 v[50:51], v[0:1]
	v_mov_b64_e32 v[46:47], v[12:13]
	v_mov_b64_e32 v[44:45], v[10:11]
	v_mov_b64_e32 v[42:43], v[8:9]
	v_mov_b64_e32 v[40:41], v[6:7]
	v_mov_b64_e32 v[38:39], v[4:5]
	v_mov_b64_e32 v[36:37], v[2:3]
	v_mov_b64_e32 v[34:35], v[0:1]
	v_mov_b64_e32 v[30:31], v[12:13]
	v_mov_b64_e32 v[28:29], v[10:11]
	v_mov_b64_e32 v[26:27], v[8:9]
	v_mov_b64_e32 v[24:25], v[6:7]
	v_mov_b64_e32 v[22:23], v[4:5]
	v_mov_b64_e32 v[20:21], v[2:3]
	v_mov_b64_e32 v[18:19], v[0:1]
	v_mov_b64_e32 v[16:17], v[14:15]
	s_add_i32 s82, s64, s82
	s_mov_b32 s83, 0
	s_mov_b32 s84, 0
	s_mov_b32 s85, 0x10000
	v_mov_b64_e32 v[14:15], v[12:13]
	v_mov_b64_e32 v[12:13], v[10:11]
	v_mov_b64_e32 v[10:11], v[8:9]
	v_mov_b64_e32 v[8:9], v[6:7]
	v_mov_b64_e32 v[6:7], v[4:5]
	v_mov_b64_e32 v[4:5], v[2:3]
	v_mov_b64_e32 v[2:3], v[0:1]
	v_mov_b32_e32 v0, 0
	v_mov_b32_e32 v196, 0
	v_mov_b32_e32 v202, 0
	s_mov_b32 s86, 0
	v_mov_b32_e32 v66, 0
	v_mov_b32_e32 v67, v1
	v_mov_b32_e32 v68, v1
	v_mov_b32_e32 v69, v1
	v_mov_b32_e32 v70, v1
	v_mov_b32_e32 v71, v1
	v_mov_b32_e32 v72, v1
	v_mov_b32_e32 v73, v1
	v_mov_b32_e32 v74, v1
	v_mov_b32_e32 v75, v1
	v_mov_b32_e32 v76, v1
	v_mov_b32_e32 v77, v1
	v_mov_b32_e32 v78, v1
	v_mov_b32_e32 v79, v1
	v_mov_b32_e32 v80, v1
	v_mov_b32_e32 v81, v1
	s_mov_b32 s100, 0
	s_mov_b32 s98, 0xfffec000
	s_mov_b32 s99, -1
	v_lshl_add_u64 v[172:173], v[172:173], 0, s[98:99]
	s_mov_b32 s98, 0xfffcc000
	s_waitcnt vmcnt(10)
	s_mov_b32 s87, 0
	s_mov_b32 s99, 0x18000
	s_add_i32 s98, s20, 0x18000
	s_add_i32 s101, s20, 0x10000
	v_lshl_add_u64 v[208:209], v[174:175], 0, s[40:41]
	v_lshl_add_u64 v[210:211], v[172:173], 0, s[40:41]
	v_add_u32_e32 v212, v178, v162
	v_add_u32_e32 v213, v180, v162
	v_add_u32_e32 v214, v182, v162
	v_add_u32_e32 v215, v184, v162
	s_branch .LSPp_top

; #define ALAS __attribute__((address_space(3)))
; template <bool WIN> ...
;     ...
;         const int k0 = (t_lo + tr) * 64;
;         const bool skip = WIN && (k0 > qw + 31 + 128 || k0 + 63 < qw - 128);
;         if (!skip) {
;             const bool near = WIN || ((k0 - (qw + 31)) < 128 && (qw - (k0 + 63)) < 128);
;             const float cinit = near ? 0.f : (k0 > qw ? cfar_hi : cfar_lo);
;             if (__builtin_expect(cinit != cbase, 0)) { cbase = cinit; asm volatile("" ::: "memory");
; #pragma unroll
;                 for (int r = 0; r < 16; ++r) cvec[r] = cbase - m_ref; }
;             f32x16 s0, s1;
;             const ALAS unsigned char* sb = lds + (tr & (NSTG - 1)) * STAGE;
;             {
;                 bf16x8 ka[8];
; #pragma unroll
;                 for (int ds = 0; ds < 4; ++ds) { ka[2 * ds] = *(const ALAS bf16x8*)(sb + kx[ds]); ka[2 * ds + 1] = *(const ALAS bf16x8*)(sb + kx[ds] + 4096); }
;                 __builtin_amdgcn_sched_barrier(0);
;                 s0 = __builtin_amdgcn_mfma_f32_32x32x16_bf16(ka[0], qf(0), cvec, 0, 0, 0);
;                 s1 = __builtin_amdgcn_mfma_f32_32x32x16_bf16(ka[1], qf(0), cvec, 0, 0, 0);
; #pragma unroll
;                 for (int ds = 1; ds < 4; ++ds) {
;                     s0 = __builtin_amdgcn_mfma_f32_32x32x16_bf16(ka[2 * ds], qf(ds), s0, 0, 0, 0);
;                     s1 = __builtin_amdgcn_mfma_f32_32x32x16_bf16(ka[2 * ds + 1], qf(ds), s1, 0, 0, 0);
;                 }
;             }
.LSPp_skipv:
.LSPp_scal:
	s_add_i32 s64, s81, s83
	s_max_i32 s64, s64, s82
	s_cmpk_lt_i32 s64, 0x80
	s_cselect_b64 s[64:65], -1, 0
	s_cmp_gt_i32 s83, s78
	s_cselect_b32 s87, s80, s79
	s_cmp_lg_u64 s[64:65], 0
	s_cselect_b32 m0, 0, s87
	s_cmp_eq_u32 m0, s100
	s_cbranch_scc0 .LSPp_cin
.LSPp_qk:
	ds_read_b128 v[130:133], v212
	ds_read_b128 v[134:137], v212 offset:4096
	ds_read_b128 v[138:141], v213
	ds_read_b128 v[142:145], v213 offset:4096
	ds_read_b128 v[146:149], v214
	ds_read_b128 v[150:153], v214 offset:4096
	ds_read_b128 v[158:161], v215
	ds_read_b128 v[204:207], v215 offset:4096
	s_cmpk_gt_u32 s86, 124
	s_cbranch_scc1 .LSPp_qkplain
	s_mov_b32 m0, s98
	s_waitcnt lgkmcnt(0)
	v_mfma_f32_32x32x16_bf16 v[98:113], v[130:133], v[126:129], v[66:81]
	global_load_lds_dwordx4 v[174:175], off
	s_add_i32 m0, s98, 0x2000
	v_mfma_f32_32x32x16_bf16 v[82:97], v[134:137], v[126:129], v[66:81]
	global_load_lds_dwordx4 v[208:209], off
	s_add_i32 m0, s101, 0x4000
	v_mfma_f32_32x32x16_bf16 v[98:113], v[138:141], v[122:125], v[98:113]
	global_load_lds_dwordx4 v[172:173], off
	s_add_i32 m0, s101, 0x6000
	v_mfma_f32_32x32x16_bf16 v[82:97], v[142:145], v[122:125], v[82:97]
	global_load_lds_dwordx4 v[210:211], off
	v_mfma_f32_32x32x16_bf16 v[98:113], v[146:149], v[118:121], v[98:113]
	v_mfma_f32_32x32x16_bf16 v[82:97], v[150:153], v[118:121], v[82:97]
	v_mfma_f32_32x32x16_bf16 v[98:113], v[158:161], v[114:117], v[98:113]
	v_mfma_f32_32x32x16_bf16 v[82:97], v[204:207], v[114:117], v[82:97]
	s_branch .LSPp_vrd

; #define ALAS __attribute__((address_space(3)))
; template <bool WIN> ...
;     ...
;             float ls0 = 0.f, ls1 = 0.f;
;     ...
;             union PFU { u32x4 u; bf16x8 b; };
;             PFU p0, p1, p2, p3;
;             AT_EXP(s0, 0, p0);
; #pragma unroll
;             for (int kk = 0; kk < 2; ++kk)
; #pragma unroll
;                 for (int db = 0; db < NDB; ++db) vc[kk * NDB + db] = *(const ALAS bf16x8*)(sb + vx[kk + 2] + db * 4096);
;             __builtin_amdgcn_sched_barrier(0);
; #pragma unroll
;             for (int db = 0; db < NDB; ++db) o[db] = __builtin_amdgcn_mfma_f32_32x32x16_bf16(va[db], p0.b, o[db], 0, 0, 0);
;             AT_EXP(s0, 8, p1);
;             __builtin_amdgcn_sched_barrier(0);
; #pragma unroll
;             for (int db = 0; db < NDB; ++db) o[db] = __builtin_amdgcn_mfma_f32_32x32x16_bf16(va[NDB + db], p1.b, o[db], 0, 0, 0);
;             AT_EXP(s1, 0, p2);
;             __builtin_amdgcn_sched_barrier(0);
; #pragma unroll
;             for (int db = 0; db < NDB; ++db) o[db] = __builtin_amdgcn_mfma_f32_32x32x16_bf16(vc[db], p2.b, o[db], 0, 0, 0);
;             AT_EXP(s1, 8, p3);
;             __builtin_amdgcn_sched_barrier(0);
; #pragma unroll
;             for (int db = 0; db < NDB; ++db) o[db] = __builtin_amdgcn_mfma_f32_32x32x16_bf16(vc[NDB + db], p3.b, o[db], 0, 0, 0);
;             __builtin_amdgcn_sched_barrier(0);
;     ...
;             l_run += ls0 + ls1;
.LSPp_pv:
	s_cmp_eq_u32 s86, 0
	s_cbranch_scc1 .LSPp_pure
	s_waitcnt lgkmcnt(4)
	v_mfma_f32_32x32x16_bf16 v[50:65], v[146:149], v[238:241], v[50:65]
	v_exp_f32_e32 v98, v98
	v_exp_f32_e32 v99, v99
	v_mfma_f32_32x32x16_bf16 v[34:49], v[150:153], v[238:241], v[34:49]
	v_exp_f32_e32 v100, v100
	v_exp_f32_e32 v101, v101
	v_mfma_f32_32x32x16_bf16 v[18:33], v[154:157], v[238:241], v[18:33]
	v_exp_f32_e32 v102, v102
	v_exp_f32_e32 v103, v103
	v_add_f32_e32 v228, v98, v100
	v_add_f32_e32 v229, v99, v101
	v_mfma_f32_32x32x16_bf16 v[2:17], v[158:161], v[238:241], v[2:17]
	v_exp_f32_e32 v104, v104
	v_exp_f32_e32 v105, v105
	v_add_f32_e32 v228, v228, v102
	v_add_f32_e32 v229, v229, v103
	v_add3_u32 v236, s99, v183, v187
	ds_read_b128 v[146:149], v236 offset:16384
	ds_read_b128 v[150:153], v236 offset:20480
	ds_read_b128 v[154:157], v236 offset:24576
	ds_read_b128 v[158:161], v236 offset:28672
	s_waitcnt lgkmcnt(4)
	v_mfma_f32_32x32x16_bf16 v[50:65], v[130:133], v[242:245], v[50:65]
	v_exp_f32_e32 v106, v106
	v_exp_f32_e32 v107, v107
	v_add_f32_e32 v228, v228, v104
	v_add_f32_e32 v229, v229, v105
	v_cvt_pk_bf16_f32 v238, v98, v99
	v_mfma_f32_32x32x16_bf16 v[34:49], v[134:137], v[242:245], v[34:49]
	v_exp_f32_e32 v108, v108
	v_exp_f32_e32 v109, v109
	v_add_f32_e32 v228, v228, v106
	v_add_f32_e32 v229, v229, v107
	v_cvt_pk_bf16_f32 v239, v100, v101
	v_mfma_f32_32x32x16_bf16 v[18:33], v[138:141], v[242:245], v[18:33]
	v_exp_f32_e32 v110, v110
	v_exp_f32_e32 v111, v111
	v_add_f32_e32 v228, v228, v108
	v_add_f32_e32 v229, v229, v109
	v_cvt_pk_bf16_f32 v240, v102, v103
	v_mfma_f32_32x32x16_bf16 v[2:17], v[142:145], v[242:245], v[2:17]
	v_exp_f32_e32 v112, v112
	v_exp_f32_e32 v113, v113
	v_add_f32_e32 v228, v228, v110
	v_add_f32_e32 v229, v229, v111
	v_cvt_pk_bf16_f32 v241, v104, v105
	v_add3_u32 v237, s99, v190, v187
	ds_read_b128 v[130:133], v237 offset:16384
	ds_read_b128 v[134:137], v237 offset:20480
	ds_read_b128 v[138:141], v237 offset:24576
	ds_read_b128 v[142:145], v237 offset:28672
	s_waitcnt lgkmcnt(4)
	v_mfma_f32_32x32x16_bf16 v[50:65], v[146:149], v[246:249], v[50:65]
	v_exp_f32_e32 v82, v82
	v_exp_f32_e32 v83, v83
	v_add_f32_e32 v228, v228, v112
	v_add_f32_e32 v229, v229, v113
	v_cvt_pk_bf16_f32 v242, v106, v107
	v_lshl_add_u64 v[174:175], v[174:175], 0, s[60:61]
	v_lshl_add_u64 v[172:173], v[172:173], 0, s[48:49]
	v_mfma_f32_32x32x16_bf16 v[34:49], v[150:153], v[246:249], v[34:49]
	v_exp_f32_e32 v84, v84
	v_exp_f32_e32 v85, v85
	v_add_f32_e32 v228, v228, v82
	v_add_f32_e32 v229, v229, v83
	v_cvt_pk_bf16_f32 v243, v108, v109
	s_add_i32 s98, s85, 0x10000
	s_and_b32 s98, s98, 0x18000
	v_mfma_f32_32x32x16_bf16 v[18:33], v[154:157], v[246:249], v[18:33]
	v_exp_f32_e32 v86, v86
	v_exp_f32_e32 v87, v87
	v_add_f32_e32 v228, v228, v84
	v_add_f32_e32 v229, v229, v85
	v_cvt_pk_bf16_f32 v244, v110, v111
	s_add_i32 s98, s98, s20
	s_add_i32 s101, s85, 0x8000
	v_mfma_f32_32x32x16_bf16 v[2:17], v[158:161], v[246:249], v[2:17]
	v_exp_f32_e32 v88, v88
	v_exp_f32_e32 v89, v89
	v_add_f32_e32 v228, v228, v86
	v_add_f32_e32 v229, v229, v87
	v_cvt_pk_bf16_f32 v245, v112, v113
	s_and_b32 s101, s101, 0x18000
	s_add_i32 s101, s101, s20
	s_waitcnt lgkmcnt(0)
	v_mfma_f32_32x32x16_bf16 v[50:65], v[130:133], v[250:253], v[50:65]
	v_exp_f32_e32 v90, v90
	v_exp_f32_e32 v91, v91
	v_add_f32_e32 v228, v228, v88
	v_add_f32_e32 v229, v229, v89
	v_cvt_pk_bf16_f32 v246, v82, v83
	s_add_i32 s87, s85, 0xffff8000
	s_and_b32 s87, s87, 0x18000
	v_mfma_f32_32x32x16_bf16 v[34:49], v[134:137], v[250:253], v[34:49]
	v_exp_f32_e32 v92, v92
	v_exp_f32_e32 v93, v93
	v_add_f32_e32 v228, v228, v90
	v_add_f32_e32 v229, v229, v91
	v_cvt_pk_bf16_f32 v247, v84, v85
	s_add_i32 s99, s85, 0xffff0000
	s_and_b32 s99, s99, 0x18000
	v_mfma_f32_32x32x16_bf16 v[18:33], v[138:141], v[250:253], v[18:33]
	v_exp_f32_e32 v94, v94
	v_exp_f32_e32 v95, v95
	v_add_f32_e32 v228, v228, v92
	v_add_f32_e32 v229, v229, v93
	v_cvt_pk_bf16_f32 v248, v86, v87
	v_lshl_add_u64 v[208:209], v[174:175], 0, s[40:41]
	v_lshl_add_u64 v[210:211], v[172:173], 0, s[40:41]
	v_mfma_f32_32x32x16_bf16 v[2:17], v[142:145], v[250:253], v[2:17]
	v_exp_f32_e32 v96, v96
	v_exp_f32_e32 v97, v97
	v_add_f32_e32 v228, v228, v94
	v_add_f32_e32 v229, v229, v95
	v_cvt_pk_bf16_f32 v249, v88, v89
	v_add3_u32 v212, s87, v178, v162
	v_add3_u32 v213, s87, v180, v162
	v_add3_u32 v214, s87, v182, v162
	v_add_f32_e32 v228, v228, v96
	v_add_f32_e32 v229, v229, v97
	v_cvt_pk_bf16_f32 v250, v90, v91
	v_cvt_pk_bf16_f32 v251, v92, v93
	v_cvt_pk_bf16_f32 v252, v94, v95
	v_cvt_pk_bf16_f32 v253, v96, v97
	v_add3_u32 v215, s87, v184, v162
	v_add_f32_e32 v228, v228, v229
	v_cmp_nge_f32_e32 vcc, 0x53800000, v228
	s_cbranch_vccnz .LSPp_redo
	s_add_i32 s86, s86, 1
	s_add_i32 s85, s85, 0x8000
	s_addk_i32 s84, 0x100
	s_add_i32 s83, s83, 64
	s_sub_i32 s82, s82, 64
	v_add_f32_e32 v0, v0, v228
	s_cmpk_eq_u32 s84, 0x8000
	s_cbranch_scc0 .LSPp_top
	s_branch .LSPp_exit
; template <bool WIN> ...
;     ...
;             {
;                 bf16x8 ka[8];
; #pragma unroll
;                 for (int ds = 0; ds < 4; ++ds) { ka[2 * ds] = *(const ALAS bf16x8*)(sb + kx[ds]); ka[2 * ds + 1] = *(const ALAS bf16x8*)(sb + kx[ds] + 4096); }
;                 __builtin_amdgcn_sched_barrier(0);
;                 s0 = __builtin_amdgcn_mfma_f32_32x32x16_bf16(ka[0], qf(0), cvec, 0, 0, 0);
;                 s1 = __builtin_amdgcn_mfma_f32_32x32x16_bf16(ka[1], qf(0), cvec, 0, 0, 0);
; #pragma unroll
;                 for (int ds = 1; ds < 4; ++ds) {
;                     s0 = __builtin_amdgcn_mfma_f32_32x32x16_bf16(ka[2 * ds], qf(ds), s0, 0, 0, 0);
;                     s1 = __builtin_amdgcn_mfma_f32_32x32x16_bf16(ka[2 * ds + 1], qf(ds), s1, 0, 0, 0);
;                 }
;             }
;             bf16x8 va[2 * NDB], vc[2 * NDB];
; #pragma unroll
;             for (int kk = 0; kk < 2; ++kk)
; #pragma unroll
;                 for (int db = 0; db < NDB; ++db) va[kk * NDB + db] = *(const ALAS bf16x8*)(sb + vx[kk] + db * 4096);
;     ...
;             float ls0 = 0.f, ls1 = 0.f;
;     ...
;             union PFU { u32x4 u; bf16x8 b; };
;             PFU p0, p1, p2, p3;
;             AT_EXP(s0, 0, p0);
; #pragma unroll
;             for (int kk = 0; kk < 2; ++kk)
; #pragma unroll
;                 for (int db = 0; db < NDB; ++db) vc[kk * NDB + db] = *(const ALAS bf16x8*)(sb + vx[kk + 2] + db * 4096);
;             __builtin_amdgcn_sched_barrier(0);
; #pragma unroll
;             for (int db = 0; db < NDB; ++db) o[db] = __builtin_amdgcn_mfma_f32_32x32x16_bf16(va[db], p0.b, o[db], 0, 0, 0);
;             AT_EXP(s0, 8, p1);
;             __builtin_amdgcn_sched_barrier(0);
; #pragma unroll
;             for (int db = 0; db < NDB; ++db) o[db] = __builtin_amdgcn_mfma_f32_32x32x16_bf16(va[NDB + db], p1.b, o[db], 0, 0, 0);
;             AT_EXP(s1, 0, p2);
;             __builtin_amdgcn_sched_barrier(0);
; #pragma unroll
;             for (int db = 0; db < NDB; ++db) o[db] = __builtin_amdgcn_mfma_f32_32x32x16_bf16(vc[db], p2.b, o[db], 0, 0, 0);
;             AT_EXP(s1, 8, p3);
;             __builtin_amdgcn_sched_barrier(0);
; #pragma unroll
;             for (int db = 0; db < NDB; ++db) o[db] = __builtin_amdgcn_mfma_f32_32x32x16_bf16(vc[NDB + db], p3.b, o[db], 0, 0, 0);
;             __builtin_amdgcn_sched_barrier(0);
;     ...
;             l_run += ls0 + ls1;
.LSPp_pure:
	v_lshl_add_u64 v[174:175], v[174:175], 0, s[60:61]
	v_lshl_add_u64 v[172:173], v[172:173], 0, s[48:49]
	s_add_i32 s98, s85, 0x10000
	s_and_b32 s98, s98, 0x18000
	s_add_i32 s98, s98, s20
	s_add_i32 s101, s85, 0x8000
	s_and_b32 s101, s101, 0x18000
	s_add_i32 s101, s101, s20
	s_add_i32 s87, s85, 0xffff8000
	s_and_b32 s87, s87, 0x18000
	s_add_i32 s99, s85, 0xffff0000
	s_and_b32 s99, s99, 0x18000
	v_lshl_add_u64 v[208:209], v[174:175], 0, s[40:41]
	v_lshl_add_u64 v[210:211], v[172:173], 0, s[40:41]
	v_add3_u32 v212, s87, v178, v162
	v_add3_u32 v213, s87, v180, v162
	v_add3_u32 v214, s87, v182, v162
	v_add3_u32 v215, s87, v184, v162
	v_exp_f32_e32 v98, v98
	v_exp_f32_e32 v99, v99
	v_exp_f32_e32 v100, v100
	v_exp_f32_e32 v101, v101
	v_exp_f32_e32 v102, v102
	v_exp_f32_e32 v103, v103
	v_exp_f32_e32 v104, v104
	v_exp_f32_e32 v105, v105
	v_cvt_pk_bf16_f32 v238, v98, v99
	v_cvt_pk_bf16_f32 v239, v100, v101
	v_cvt_pk_bf16_f32 v240, v102, v103
	v_cvt_pk_bf16_f32 v241, v104, v105
	v_mov_b32_e32 v228, v98
	v_mov_b32_e32 v229, v102
	v_add_f32_e32 v228, v228, v99
	v_add_f32_e32 v229, v229, v103
	v_add_f32_e32 v228, v228, v100
	v_add_f32_e32 v229, v229, v104
	v_add_f32_e32 v228, v228, v101
	v_add_f32_e32 v229, v229, v105
	v_exp_f32_e32 v106, v106
	v_exp_f32_e32 v107, v107
	v_exp_f32_e32 v108, v108
	v_exp_f32_e32 v109, v109
	v_exp_f32_e32 v110, v110
	v_exp_f32_e32 v111, v111
	v_exp_f32_e32 v112, v112
	v_exp_f32_e32 v113, v113
	v_cvt_pk_bf16_f32 v242, v106, v107
	v_cvt_pk_bf16_f32 v243, v108, v109
	v_cvt_pk_bf16_f32 v244, v110, v111
	v_cvt_pk_bf16_f32 v245, v112, v113
	v_add_f32_e32 v228, v228, v106
	v_add_f32_e32 v229, v229, v110
	v_add_f32_e32 v228, v228, v107
	v_add_f32_e32 v229, v229, v111
	v_add_f32_e32 v228, v228, v108
	v_add_f32_e32 v229, v229, v112
	v_add_f32_e32 v228, v228, v109
	v_add_f32_e32 v229, v229, v113
	v_exp_f32_e32 v82, v82
	v_exp_f32_e32 v83, v83
	v_exp_f32_e32 v84, v84
	v_exp_f32_e32 v85, v85
	v_exp_f32_e32 v86, v86
	v_exp_f32_e32 v87, v87
	v_exp_f32_e32 v88, v88
	v_exp_f32_e32 v89, v89
	v_cvt_pk_bf16_f32 v246, v82, v83
	v_cvt_pk_bf16_f32 v247, v84, v85
	v_cvt_pk_bf16_f32 v248, v86, v87
	v_cvt_pk_bf16_f32 v249, v88, v89
	v_add_f32_e32 v228, v228, v82
	v_add_f32_e32 v229, v229, v86
	v_add_f32_e32 v228, v228, v83
	v_add_f32_e32 v229, v229, v87
	v_add_f32_e32 v228, v228, v84
	v_add_f32_e32 v229, v229, v88
	v_add_f32_e32 v228, v228, v85
	v_add_f32_e32 v229, v229, v89
	v_exp_f32_e32 v90, v90
	v_exp_f32_e32 v91, v91
	v_exp_f32_e32 v92, v92
	v_exp_f32_e32 v93, v93
	v_exp_f32_e32 v94, v94
	v_exp_f32_e32 v95, v95
	v_exp_f32_e32 v96, v96
	v_exp_f32_e32 v97, v97
	v_cvt_pk_bf16_f32 v250, v90, v91
	v_cvt_pk_bf16_f32 v251, v92, v93
	v_cvt_pk_bf16_f32 v252, v94, v95
	v_cvt_pk_bf16_f32 v253, v96, v97
	v_add_f32_e32 v228, v228, v90
	v_add_f32_e32 v229, v229, v94
	v_add_f32_e32 v228, v228, v91
	v_add_f32_e32 v229, v229, v95
	v_add_f32_e32 v228, v228, v92
	v_add_f32_e32 v229, v229, v96
	v_add_f32_e32 v228, v228, v93
	v_add_f32_e32 v229, v229, v97
	v_add_f32_e32 v228, v228, v229
	v_cmp_nge_f32_e32 vcc, 0x53800000, v228
	s_cbranch_vccnz .LSPp_redo
	s_add_i32 s86, s86, 1
	s_add_i32 s85, s85, 0x8000
	s_addk_i32 s84, 0x100
	s_add_i32 s83, s83, 64
	s_sub_i32 s82, s82, 64
	v_add_f32_e32 v0, v0, v228
	s_cmpk_eq_u32 s84, 0x8000
	s_cbranch_scc0 .LSPp_top
	s_branch .LSPp_exit
.LSPp_redo:
	s_add_i32 s87, s87, 0x18000
	s_and_b32 s87, s87, 0x18000
	v_add3_u32 v203, s87, v178, v162
	ds_read_b128 v[130:133], v203
	ds_read_b128 v[134:137], v203 offset:4096
	v_add3_u32 v203, s87, v180, v162
	ds_read_b128 v[138:141], v203
	ds_read_b128 v[142:145], v203 offset:4096
	v_add3_u32 v203, s87, v182, v162
	ds_read_b128 v[146:149], v203
	ds_read_b128 v[150:153], v203 offset:4096
	v_add3_u32 v203, s87, v184, v162
	ds_read_b128 v[158:161], v203
	ds_read_b128 v[204:207], v203 offset:4096
	s_waitcnt lgkmcnt(0)
	v_mfma_f32_32x32x16_bf16 v[98:113], v[130:133], v[126:129], v[66:81]
	v_mfma_f32_32x32x16_bf16 v[82:97], v[134:137], v[126:129], v[66:81]
	v_mfma_f32_32x32x16_bf16 v[98:113], v[138:141], v[122:125], v[98:113]
	v_mfma_f32_32x32x16_bf16 v[82:97], v[142:145], v[122:125], v[82:97]
	v_mfma_f32_32x32x16_bf16 v[98:113], v[146:149], v[118:121], v[98:113]
	v_mfma_f32_32x32x16_bf16 v[82:97], v[150:153], v[118:121], v[82:97]
	v_mfma_f32_32x32x16_bf16 v[98:113], v[158:161], v[114:117], v[98:113]
	v_mfma_f32_32x32x16_bf16 v[82:97], v[204:207], v[114:117], v[82:97]
	s_nop 7
	s_nop 7
	s_andn2_b64 vcc, exec, s[64:65]
	s_cbranch_vccnz .LSPp_redomax
	v_add_u32_e32 v203, s84, v171
	v_add_u32_e32 v204, 0x23b80, v203
	v_add_u32_e32 v206, 0x23c00, v203
	v_add_u32_e32 v210, 0x23c08, v203
	v_add_u32_e32 v208, 0x23b88, v203
	v_add_u32_e32 v218, 0x23c10, v203
	v_add_u32_e32 v212, 0x23b90, v203
	v_add_u32_e32 v216, 0x23c18, v203
	v_add_u32_e32 v214, 0x23b98, v203
	ds_read2_b32 v[204:205], v204 offset1:1
	ds_read2_b32 v[206:207], v206 offset1:1
	ds_read2_b32 v[208:209], v208 offset1:1
	ds_read2_b32 v[210:211], v210 offset1:1
	ds_read2_b32 v[212:213], v212 offset1:1
	ds_read2_b32 v[214:215], v214 offset1:1
	ds_read2_b32 v[216:217], v216 offset1:1
	ds_read2_b32 v[218:219], v218 offset1:1
	v_add_u32_e32 v220, 0x23bc0, v203
	v_add_u32_e32 v222, 0x23c40, v203
	v_add_u32_e32 v226, 0x23c48, v203
	v_add_u32_e32 v224, 0x23bc8, v203
	v_add_u32_e32 v228, 0x23bd0, v203
	v_add_u32_e32 v234, 0x23c58, v203
	ds_read2_b32 v[220:221], v220 offset1:1
	ds_read2_b32 v[222:223], v222 offset1:1
	ds_read2_b32 v[224:225], v224 offset1:1
	ds_read2_b32 v[226:227], v226 offset1:1
	v_add_u32_e32 v231, 0x23c50, v203
	v_add_u32_e32 v203, 0x23bd8, v203
	ds_read2_b32 v[228:229], v228 offset1:1
	ds_read2_b32 v[232:233], v203 offset1:1
	ds_read2_b32 v[234:235], v234 offset1:1
	ds_read2_b32 v[236:237], v231 offset1:1
	s_waitcnt lgkmcnt(10)
	v_pk_add_f32 v[104:105], v[104:105], v[214:215]
	v_pk_add_f32 v[102:103], v[102:103], v[212:213]
	v_pk_add_f32 v[100:101], v[100:101], v[208:209]
	s_waitcnt lgkmcnt(2)
	v_pk_add_f32 v[112:113], v[112:113], v[232:233]
	v_pk_add_f32 v[110:111], v[110:111], v[228:229]
	v_pk_add_f32 v[108:109], v[108:109], v[224:225]
	v_pk_add_f32 v[106:107], v[106:107], v[220:221]
	v_pk_add_f32 v[98:99], v[98:99], v[204:205]
	v_pk_add_f32 v[88:89], v[88:89], v[216:217]
	v_pk_add_f32 v[86:87], v[86:87], v[218:219]
	v_pk_add_f32 v[84:85], v[84:85], v[210:211]
	s_waitcnt lgkmcnt(1)
	v_pk_add_f32 v[96:97], v[96:97], v[234:235]
	s_waitcnt lgkmcnt(0)
	v_pk_add_f32 v[94:95], v[94:95], v[236:237]
	v_pk_add_f32 v[92:93], v[92:93], v[226:227]
	v_pk_add_f32 v[90:91], v[90:91], v[222:223]
	v_pk_add_f32 v[82:83], v[82:83], v[206:207]

; #define ALAS __attribute__((address_space(3)))
; template <bool WIN> ...
;     ...
;             float ls0 = 0.f, ls1 = 0.f;
;     ...
;             union PFU { u32x4 u; bf16x8 b; };
;             PFU p0, p1, p2, p3;
;             AT_EXP(s0, 0, p0);
; #pragma unroll
;             for (int kk = 0; kk < 2; ++kk)
; #pragma unroll
;                 for (int db = 0; db < NDB; ++db) vc[kk * NDB + db] = *(const ALAS bf16x8*)(sb + vx[kk + 2] + db * 4096);
;             __builtin_amdgcn_sched_barrier(0);
; #pragma unroll
;             for (int db = 0; db < NDB; ++db) o[db] = __builtin_amdgcn_mfma_f32_32x32x16_bf16(va[db], p0.b, o[db], 0, 0, 0);
;             AT_EXP(s0, 8, p1);
;             __builtin_amdgcn_sched_barrier(0);
; #pragma unroll
;             for (int db = 0; db < NDB; ++db) o[db] = __builtin_amdgcn_mfma_f32_32x32x16_bf16(va[NDB + db], p1.b, o[db], 0, 0, 0);
;             AT_EXP(s1, 0, p2);
;             __builtin_amdgcn_sched_barrier(0);
; #pragma unroll
;             for (int db = 0; db < NDB; ++db) o[db] = __builtin_amdgcn_mfma_f32_32x32x16_bf16(vc[db], p2.b, o[db], 0, 0, 0);
;             AT_EXP(s1, 8, p3);
;             __builtin_amdgcn_sched_barrier(0);
; #pragma unroll
;             for (int db = 0; db < NDB; ++db) o[db] = __builtin_amdgcn_mfma_f32_32x32x16_bf16(vc[NDB + db], p3.b, o[db], 0, 0, 0);
;             __builtin_amdgcn_sched_barrier(0);
;     ...
;             l_run += ls0 + ls1;
.LSPp_pure2:
	s_add_i32 s87, s87, 0x8000
	s_and_b32 s87, s87, 0x18000
	v_lshl_add_u64 v[208:209], v[174:175], 0, s[40:41]
	v_lshl_add_u64 v[210:211], v[172:173], 0, s[40:41]
	v_add3_u32 v212, s87, v178, v162
	v_add3_u32 v213, s87, v180, v162
	v_add3_u32 v214, s87, v182, v162
	v_add3_u32 v215, s87, v184, v162
	v_exp_f32_e32 v98, v98
	v_exp_f32_e32 v99, v99
	v_exp_f32_e32 v100, v100
	v_exp_f32_e32 v101, v101
	v_exp_f32_e32 v102, v102
	v_exp_f32_e32 v103, v103
	v_exp_f32_e32 v104, v104
	v_exp_f32_e32 v105, v105
	v_cvt_pk_bf16_f32 v238, v98, v99
	v_cvt_pk_bf16_f32 v239, v100, v101
	v_cvt_pk_bf16_f32 v240, v102, v103
	v_cvt_pk_bf16_f32 v241, v104, v105
	v_mov_b32_e32 v228, v98
	v_mov_b32_e32 v229, v102
	v_add_f32_e32 v228, v228, v99
	v_add_f32_e32 v229, v229, v103
	v_add_f32_e32 v228, v228, v100
	v_add_f32_e32 v229, v229, v104
	v_add_f32_e32 v228, v228, v101
	v_add_f32_e32 v229, v229, v105
	v_exp_f32_e32 v106, v106
	v_exp_f32_e32 v107, v107
	v_exp_f32_e32 v108, v108
	v_exp_f32_e32 v109, v109
	v_exp_f32_e32 v110, v110
	v_exp_f32_e32 v111, v111
	v_exp_f32_e32 v112, v112
	v_exp_f32_e32 v113, v113
	v_cvt_pk_bf16_f32 v242, v106, v107
	v_cvt_pk_bf16_f32 v243, v108, v109
	v_cvt_pk_bf16_f32 v244, v110, v111
	v_cvt_pk_bf16_f32 v245, v112, v113
	v_add_f32_e32 v228, v228, v106
	v_add_f32_e32 v229, v229, v110
	v_add_f32_e32 v228, v228, v107
	v_add_f32_e32 v229, v229, v111
	v_add_f32_e32 v228, v228, v108
	v_add_f32_e32 v229, v229, v112
	v_add_f32_e32 v228, v228, v109
	v_add_f32_e32 v229, v229, v113
	v_exp_f32_e32 v82, v82
	v_exp_f32_e32 v83, v83
	v_exp_f32_e32 v84, v84
	v_exp_f32_e32 v85, v85
	v_exp_f32_e32 v86, v86
	v_exp_f32_e32 v87, v87
	v_exp_f32_e32 v88, v88
	v_exp_f32_e32 v89, v89
	v_cvt_pk_bf16_f32 v246, v82, v83
	v_cvt_pk_bf16_f32 v247, v84, v85
	v_cvt_pk_bf16_f32 v248, v86, v87
	v_cvt_pk_bf16_f32 v249, v88, v89
	v_add_f32_e32 v228, v228, v82
	v_add_f32_e32 v229, v229, v86
	v_add_f32_e32 v228, v228, v83
	v_add_f32_e32 v229, v229, v87
	v_add_f32_e32 v228, v228, v84
	v_add_f32_e32 v229, v229, v88
	v_add_f32_e32 v228, v228, v85
	v_add_f32_e32 v229, v229, v89
	v_exp_f32_e32 v90, v90
	v_exp_f32_e32 v91, v91
	v_exp_f32_e32 v92, v92
	v_exp_f32_e32 v93, v93
	v_exp_f32_e32 v94, v94
	v_exp_f32_e32 v95, v95
	v_exp_f32_e32 v96, v96
	v_exp_f32_e32 v97, v97
	v_cvt_pk_bf16_f32 v250, v90, v91
	v_cvt_pk_bf16_f32 v251, v92, v93
	v_cvt_pk_bf16_f32 v252, v94, v95
	v_cvt_pk_bf16_f32 v253, v96, v97
	v_add_f32_e32 v228, v228, v90
	v_add_f32_e32 v229, v229, v94
	v_add_f32_e32 v228, v228, v91
	v_add_f32_e32 v229, v229, v95
	v_add_f32_e32 v228, v228, v92
	v_add_f32_e32 v229, v229, v96
	v_add_f32_e32 v228, v228, v93
	v_add_f32_e32 v229, v229, v97
	v_add_f32_e32 v228, v228, v229
	s_add_i32 s86, s86, 1
	s_add_i32 s85, s85, 0x8000
	s_addk_i32 s84, 0x100
	s_add_i32 s83, s83, 64
	s_sub_i32 s82, s82, 64
	v_add_f32_e32 v0, v0, v228
	s_cmpk_eq_u32 s84, 0x8000
	s_cbranch_scc0 .LSPp_top
	s_branch .LSPp_exit

; template <bool WIN> ...
;     ...
;             const float cinit = near ? 0.f : (k0 > qw ? cfar_hi : cfar_lo);
;             if (__builtin_expect(cinit != cbase, 0)) { cbase = cinit; asm volatile("" ::: "memory");
; #pragma unroll
;                 for (int r = 0; r < 16; ++r) cvec[r] = cbase - m_ref; }
.LSPp_cin:
	v_mov_b32_e32 v98, m0
	s_mov_b32 s100, m0
	v_sub_f32_e32 v82, v98, v196
	v_mov_b32_e32 v202, v98
	v_mov_b32_e32 v66, v82
	v_mov_b32_e32 v67, v82
	v_mov_b32_e32 v68, v82
	v_mov_b32_e32 v69, v82
	v_mov_b32_e32 v70, v82
	v_mov_b32_e32 v71, v82
	v_mov_b32_e32 v72, v82
	v_mov_b32_e32 v73, v82
	v_mov_b32_e32 v74, v82
	v_mov_b32_e32 v75, v82
	v_mov_b32_e32 v76, v82
	v_mov_b32_e32 v77, v82
	v_mov_b32_e32 v78, v82
	v_mov_b32_e32 v79, v82
	v_mov_b32_e32 v80, v82
	v_mov_b32_e32 v81, v82
	s_branch .LSPp_qk

; __device__ __forceinline__ int pi32(int r) { return (r & ~12) | ((r & 4) << 1) | ((r & 8) >> 1); }
; #define AT_DMA(tr) do { const unsigned sb_ = (unsigned)__builtin_amdgcn_readfirstlane(dk + (((tr) & (NSTG - 1)) * STAGE)); const size_t ko_ = (size_t)(tr) * 26 * 4096, vo_ = (size_t)(tr) * 640 * 64; \
;         glds16(kg + ko_, sb_ + OFF_K0); if (!WIN) glds16(kg + ko_ + 4096, sb_ + OFF_K1); glds16(vg + vo_, sb_ + OFF_V); if (!WIN) glds16(vg + vo_ + 64 * 64, sb_ + OFF_V + 8192); } while (0)
; template <bool WIN> ...
;     ...
;     const bf16_t* kg = QK + ((size_t)((seq_base >> 6) + t_lo) * 26 * 64 + drow) * 64 + dch * 8 + kcol0 * 64;
;     const bf16_t* vg = VT + ((size_t)((seq_base >> 6) + t_lo) * 640 + vrow0 + drow) * 64 + dch * 8;
;     const unsigned dk = ldsb + wid * 1024;
;     ...
;     constexpr int NPW = WIN ? 2 : 4;
;     bf16x8 qfr[4];
;     { const int qrow = seq_base + qw + l31; const bf16_t* qp = QK + ((size_t)((qrow >> 6) * 26 + (qcol >> 6)) * 64 + (qrow & 63)) * 64 + hi * 8;
; #pragma unroll
;       for (int ds = 0; ds < 4; ++ds) qfr[ds] = *(const bf16x8*)(qp + ds * 16); }
;     ...
;     AT_DMA(0); if (NT > 1) AT_DMA(1); if (NT > 2) AT_DMA(2);
;     constexpr float THR = 8.0f;
;     float m_ref = WIN ? sinkp[2 * hsel + half] * LOG2E : 0.f;
;     float l_run = (WIN && hi == 0) ? 1.f : 0.f;
;     float cbase = 0.f;
;     f32x16 cvec;
; #pragma unroll
;     for (int r = 0; r < 16; ++r) cvec[r] = cbase - m_ref;
;     f32x16 o[NDB];
; #pragma unroll
;     for (int db = 0; db < NDB; ++db)
; #pragma unroll
;         for (int r = 0; r < 16; ++r) o[db][r] = 0.f;
;     const int krow = pi32(l31), fK = (krow >> 1) & 7, fV = (l31 >> 1) & 7;
;     int kx[4], vx[4];
; #pragma unroll
;     for (int c = 0; c < 4; ++c) { kx[c] = (WIN ? OFF_K0 : (half ? OFF_K1 : OFF_K0)) + krow * 128 + (((2 * c + hi) ^ fK) << 4); vx[c] = OFF_V + l31 * 128 + (((2 * c + hi) ^ fV) << 4); }
;     const int qabs = qw + l31;
;     const float cfar_lo = __uint_as_float(__builtin_amdgcn_readfirstlane(__float_as_uint(lut[0]))), cfar_hi = __uint_as_float(__builtin_amdgcn_readfirstlane(__float_as_uint(lut[LUTW - 1])));
;     asm volatile("" : "+v"(qfr[0]), "+v"(qfr[1]), "+v"(qfr[2]), "+v"(qfr[3]));
.LBB0_268:
	v_readfirstlane_b32 s33, v230
	s_lshl_b32 s26, s25, 13
	s_bfe_u32 s27, s33, 0x20006
	s_add_i32 s26, s26, s23
	s_lshl_b32 s28, s27, 5
	s_and_b32 s26, s26, 0xfffff800
	s_or_b32 s28, s28, s22
	s_add_i32 s29, s26, 0x10000
	s_lshr_b32 s26, s33, 8
	v_or_b32_e32 v10, s28, v185
	v_or_b32_e32 v170, s29, v10
	s_add_i32 s30, s26, s66
	v_ashrrev_i32_e32 v2, 6, v170
	v_mov_b32_e32 v0, s30
	v_mad_u64_u32 v[2:3], s[30:31], v2, 26, v[0:1]
	v_ashrrev_i32_e32 v3, 31, v2
	v_lshlrev_b64 v[2:3], 13, v[2:3]
	v_lshlrev_b32_e32 v0, 7, v10
	v_lshl_add_u64 v[2:3], s[6:7], 0, v[2:3]
	v_and_b32_e32 v4, 0x1f80, v0
	v_mov_b32_e32 v5, v1
	v_lshl_add_u64 v[2:3], v[2:3], 0, v[4:5]
	v_lshl_add_u64 v[2:3], v[2:3], 0, v[164:165]
	global_load_dwordx4 v[114:117], v[2:3], off offset:96
	global_load_dwordx4 v[118:121], v[2:3], off offset:64
	global_load_dwordx4 v[122:125], v[2:3], off offset:32
	global_load_dwordx4 v[126:129], v[2:3], off
	s_lshr_b32 s62, s33, 6
	s_lshr_b32 s30, s33, 4
	v_lshl_or_b32 v0, s62, 3, v188
	s_and_b32 s30, s30, 4
	s_ashr_i32 s76, s29, 6
	v_bitop3_b32 v4, s30, v186, v189 bitop3:0x36
	v_mad_i64_i32 v[2:3], s[30:31], s76, v194, v[0:1]
	v_lshlrev_b64 v[2:3], 7, v[2:3]
	v_lshl_add_u64 v[2:3], s[6:7], 0, v[2:3]
	v_lshlrev_b32_e32 v4, 4, v4
	s_mul_hi_i32 s31, s76, 0x280
	s_mul_i32 s30, s76, 0x280
	v_lshl_add_u64 v[2:3], v[2:3], 0, v[4:5]
	s_or_b64 s[30:31], s[30:31], s[12:13]
	v_lshl_add_u64 v[2:3], v[2:3], 0, s[18:19]
	v_lshl_add_u64 v[6:7], s[30:31], 0, v[0:1]
	s_lshl_b32 s29, s62, 10
	v_lshlrev_b64 v[6:7], 7, v[6:7]
	v_lshl_add_u64 v[8:9], v[2:3], 0, s[36:37]
	s_add_i32 s29, s29, 0
	s_mov_b32 s30, m0
	s_mov_b32 m0, s29
	s_nop 0
	global_load_lds_dwordx4 v[8:9], off
	s_mov_b32 m0, s30
	v_lshl_add_u64 v[6:7], s[4:5], 0, v[6:7]
	v_lshl_add_u64 v[8:9], v[2:3], 0, s[38:39]
	s_add_i32 s30, s29, 0x2000
	s_mov_b32 s31, m0
	s_mov_b32 m0, s30
	s_nop 0
	global_load_lds_dwordx4 v[8:9], off
	s_mov_b32 m0, s31
	v_lshl_add_u64 v[6:7], v[6:7], 0, v[4:5]
	s_add_i32 s30, s29, 0x4000
	s_mov_b32 s31, m0
	s_mov_b32 m0, s30
	s_nop 0
	global_load_lds_dwordx4 v[6:7], off
	s_mov_b32 m0, s31
	v_lshl_add_u64 v[8:9], v[6:7], 0, s[40:41]
	s_add_i32 s30, s29, 0x6000
	s_mov_b32 s31, m0
	s_mov_b32 m0, s30
	s_nop 0
	global_load_lds_dwordx4 v[8:9], off
	s_mov_b32 m0, s31
	s_add_i32 s30, s29, 0x8000
	v_lshl_add_u64 v[8:9], v[2:3], 0, s[42:43]
	s_mov_b32 s31, m0
	s_mov_b32 m0, s30
	s_nop 0
	global_load_lds_dwordx4 v[8:9], off
	s_mov_b32 m0, s31
	v_lshl_add_u64 v[8:9], v[2:3], 0, s[46:47]
	s_add_i32 s30, s29, 0xa000
	s_mov_b32 s31, m0
	s_mov_b32 m0, s30
	s_nop 0
	global_load_lds_dwordx4 v[8:9], off
	s_mov_b32 m0, s31
	v_lshl_add_u64 v[8:9], v[6:7], 0, s[48:49]
	s_add_i32 s30, s29, 0xc000
	s_mov_b32 s31, m0
	s_mov_b32 m0, s30
	s_nop 0
	global_load_lds_dwordx4 v[8:9], off
	s_mov_b32 m0, s31
	v_lshl_add_u64 v[8:9], v[6:7], 0, s[50:51]
	s_add_i32 s30, s29, 0xe000
	s_mov_b32 s31, m0
	s_mov_b32 m0, s30
	s_nop 0
	global_load_lds_dwordx4 v[8:9], off
	s_mov_b32 m0, s31
	s_add_i32 s30, s29, 0x10000
	v_lshl_add_u64 v[8:9], v[2:3], 0, s[52:53]
	s_mov_b32 s31, m0
	s_mov_b32 m0, s30
	s_nop 0
	global_load_lds_dwordx4 v[8:9], off
	s_mov_b32 m0, s31
	v_lshl_add_u64 v[2:3], v[2:3], 0, s[54:55]
	s_add_i32 s30, s29, 0x12000
	s_mov_b32 s31, m0
	s_mov_b32 m0, s30
	s_nop 0
	global_load_lds_dwordx4 v[2:3], off
	s_mov_b32 m0, s31
	v_lshl_add_u64 v[2:3], v[6:7], 0, s[56:57]
	s_add_i32 s30, s29, 0x14000
	v_lshl_add_u64 v[2:3], v[6:7], 0, s[58:59]
	s_add_i32 s30, s29, 0x16000
	ds_read_b32 v2, v197 offset:14336
	ds_read_b32 v3, v197 offset:16124
	s_cmpk_lt_u32 s33, 0x100
	s_cselect_b64 s[62:63], -1, 0
	s_and_b64 s[30:31], s[62:63], exec
	s_cselect_b32 s30, 0, 0x2000
	v_or_b32_e32 v162, s30, v177
	s_waitcnt lgkmcnt(1)
	v_readfirstlane_b32 s30, v2
	s_waitcnt lgkmcnt(0)
	v_readfirstlane_b32 s31, v3
	v_lshlrev_b64 v[2:3], 7, v[0:1]
	v_mad_i64_i32 v[6:7], s[64:65], s76, v198, v[2:3]
	v_mad_i64_i32 v[2:3], s[64:65], s76, v199, v[2:3]
	v_or_b32_e32 v6, v6, v4
	v_or_b32_e32 v2, v2, v4
	v_lshlrev_b32_e32 v0, 2, v10
	v_mov_b32_e32 v14, v1
	v_mov_b32_e32 v15, v1
	v_lshl_add_u64 v[172:173], s[20:21], 0, v[6:7]
	v_lshl_add_u64 v[174:175], s[16:17], 0, v[2:3]
	v_sub_u32_e32 v171, v195, v0
	v_mov_b32_e32 v0, v1
	v_mov_b32_e32 v2, v1
	v_mov_b32_e32 v3, v1
	v_mov_b32_e32 v4, v1
	v_mov_b32_e32 v6, v1
	v_mov_b32_e32 v7, v1
	v_mov_b32_e32 v8, v1
	v_mov_b32_e32 v9, v1
	v_mov_b32_e32 v10, v1
	v_mov_b32_e32 v11, v1
	v_mov_b32_e32 v12, v1
	v_mov_b32_e32 v13, v1
	v_mov_b64_e32 v[64:65], v[14:15]
	v_mov_b64_e32 v[48:49], v[14:15]
	v_mov_b64_e32 v[32:33], v[14:15]
	v_mov_b64_e32 v[62:63], v[12:13]
	v_mov_b64_e32 v[60:61], v[10:11]
	v_mov_b64_e32 v[58:59], v[8:9]
	v_mov_b64_e32 v[56:57], v[6:7]
	v_mov_b64_e32 v[54:55], v[4:5]
	v_mov_b64_e32 v[52:53], v[2:3]
	v_mov_b64_e32 v[50:51], v[0:1]
	v_mov_b64_e32 v[46:47], v[12:13]
	v_mov_b64_e32 v[44:45], v[10:11]
	v_mov_b64_e32 v[42:43], v[8:9]
	v_mov_b64_e32 v[40:41], v[6:7]
	v_mov_b64_e32 v[38:39], v[4:5]
	v_mov_b64_e32 v[36:37], v[2:3]
	v_mov_b64_e32 v[34:35], v[0:1]
	v_mov_b64_e32 v[30:31], v[12:13]
	v_mov_b64_e32 v[28:29], v[10:11]
	v_mov_b64_e32 v[26:27], v[8:9]
	v_mov_b64_e32 v[24:25], v[6:7]
	v_mov_b64_e32 v[22:23], v[4:5]
	v_mov_b64_e32 v[20:21], v[2:3]
	v_mov_b64_e32 v[18:19], v[0:1]
	v_mov_b64_e32 v[16:17], v[14:15]
	s_add_i32 s33, s28, 0x9f
	s_add_i32 s67, s28, 0xffffff41
	s_mov_b32 s76, 0
	s_mov_b32 s77, 0
	s_mov_b32 s78, 0x10000
	v_mov_b64_e32 v[14:15], v[12:13]
	v_mov_b64_e32 v[12:13], v[10:11]
	v_mov_b64_e32 v[10:11], v[8:9]
	v_mov_b64_e32 v[8:9], v[6:7]
	v_mov_b64_e32 v[6:7], v[4:5]
	v_mov_b64_e32 v[4:5], v[2:3]
	v_mov_b64_e32 v[2:3], v[0:1]
	v_mov_b32_e32 v0, 0
	v_mov_b32_e32 v201, 0
	v_mov_b32_e32 v202, 0
	s_mov_b32 s79, 0
	v_mov_b32_e32 v66, 0
	v_mov_b32_e32 v67, v1
	v_mov_b32_e32 v68, v1
	v_mov_b32_e32 v69, v1
	v_mov_b32_e32 v70, v1
	v_mov_b32_e32 v71, v1
	v_mov_b32_e32 v72, v1
	v_mov_b32_e32 v73, v1
	v_mov_b32_e32 v74, v1
	v_mov_b32_e32 v75, v1
	v_mov_b32_e32 v76, v1
	v_mov_b32_e32 v77, v1
	v_mov_b32_e32 v78, v1
	v_mov_b32_e32 v79, v1
	v_mov_b32_e32 v80, v1
	v_mov_b32_e32 v81, v1
	s_mov_b32 s100, 0
	s_mov_b32 s98, 0xfffec000
	s_mov_b32 s99, -1
	v_lshl_add_u64 v[172:173], v[172:173], 0, s[98:99]
	s_mov_b32 s98, 0xfffcc000
	s_waitcnt vmcnt(10)
	s_mov_b32 s80, 0
	s_mov_b32 s99, 0x18000
	s_add_i32 s98, s29, 0x18000
	s_add_i32 s101, s29, 0x10000
	v_lshl_add_u64 v[208:209], v[174:175], 0, s[40:41]
	v_lshl_add_u64 v[210:211], v[172:173], 0, s[40:41]
	v_add_u32_e32 v212, v178, v162
	v_add_u32_e32 v213, v180, v162
	v_add_u32_e32 v214, v182, v162
	v_add_u32_e32 v215, v184, v162
	s_branch .LSPs_top

; #define ALAS __attribute__((address_space(3)))
; template <bool WIN> ...
;     ...
;         const int k0 = (t_lo + tr) * 64;
;         const bool skip = WIN && (k0 > qw + 31 + 128 || k0 + 63 < qw - 128);
;         if (!skip) {
;             const bool near = WIN || ((k0 - (qw + 31)) < 128 && (qw - (k0 + 63)) < 128);
;             const float cinit = near ? 0.f : (k0 > qw ? cfar_hi : cfar_lo);
;             if (__builtin_expect(cinit != cbase, 0)) { cbase = cinit; asm volatile("" ::: "memory");
; #pragma unroll
;                 for (int r = 0; r < 16; ++r) cvec[r] = cbase - m_ref; }
;             f32x16 s0, s1;
;             const ALAS unsigned char* sb = lds + (tr & (NSTG - 1)) * STAGE;
;             {
;                 bf16x8 ka[8];
; #pragma unroll
;                 for (int ds = 0; ds < 4; ++ds) { ka[2 * ds] = *(const ALAS bf16x8*)(sb + kx[ds]); ka[2 * ds + 1] = *(const ALAS bf16x8*)(sb + kx[ds] + 4096); }
;                 __builtin_amdgcn_sched_barrier(0);
;                 s0 = __builtin_amdgcn_mfma_f32_32x32x16_bf16(ka[0], qf(0), cvec, 0, 0, 0);
;                 s1 = __builtin_amdgcn_mfma_f32_32x32x16_bf16(ka[1], qf(0), cvec, 0, 0, 0);
; #pragma unroll
;                 for (int ds = 1; ds < 4; ++ds) {
;                     s0 = __builtin_amdgcn_mfma_f32_32x32x16_bf16(ka[2 * ds], qf(ds), s0, 0, 0, 0);
;                     s1 = __builtin_amdgcn_mfma_f32_32x32x16_bf16(ka[2 * ds + 1], qf(ds), s1, 0, 0, 0);
;                 }
;             }
.LSPs_skipv:
.LSPs_scal:
	s_cmp_lt_u32 s76, s33
	s_cselect_b64 s[64:65], -1, 0
	s_cmp_gt_i32 s76, s67
	s_cselect_b64 s[80:81], -1, 0
	s_and_b64 s[64:65], s[64:65], s[80:81]
	s_cmp_gt_u32 s76, s28
	s_cselect_b32 s80, s31, s30
	s_cmp_lg_u64 s[64:65], 0
	s_cselect_b32 m0, 0, s80
	s_cmp_eq_u32 m0, s100
	s_cbranch_scc0 .LSPs_cin
.LSPs_qk:
	ds_read_b128 v[130:133], v212
	ds_read_b128 v[134:137], v212 offset:4096
	ds_read_b128 v[138:141], v213
	ds_read_b128 v[142:145], v213 offset:4096
	ds_read_b128 v[146:149], v214
	ds_read_b128 v[150:153], v214 offset:4096
	ds_read_b128 v[158:161], v215
	ds_read_b128 v[204:207], v215 offset:4096
	s_cmpk_gt_u32 s79, 28
	s_cbranch_scc1 .LSPs_qkplain
	s_mov_b32 m0, s98
	s_waitcnt lgkmcnt(0)
	v_mfma_f32_32x32x16_bf16 v[98:113], v[130:133], v[126:129], v[66:81]
	global_load_lds_dwordx4 v[174:175], off
	s_add_i32 m0, s98, 0x2000
	v_mfma_f32_32x32x16_bf16 v[82:97], v[134:137], v[126:129], v[66:81]
	global_load_lds_dwordx4 v[208:209], off
	s_add_i32 m0, s101, 0x4000
	v_mfma_f32_32x32x16_bf16 v[98:113], v[138:141], v[122:125], v[98:113]
	global_load_lds_dwordx4 v[172:173], off
	s_add_i32 m0, s101, 0x6000
	v_mfma_f32_32x32x16_bf16 v[82:97], v[142:145], v[122:125], v[82:97]
	global_load_lds_dwordx4 v[210:211], off
	v_mfma_f32_32x32x16_bf16 v[98:113], v[146:149], v[118:121], v[98:113]
	v_mfma_f32_32x32x16_bf16 v[82:97], v[150:153], v[118:121], v[82:97]
	v_mfma_f32_32x32x16_bf16 v[98:113], v[158:161], v[114:117], v[98:113]
	v_mfma_f32_32x32x16_bf16 v[82:97], v[204:207], v[114:117], v[82:97]
	s_branch .LSPs_vrd

; #define ALAS __attribute__((address_space(3)))
; template <bool WIN> ...
;     ...
;             float ls0 = 0.f, ls1 = 0.f;
;     ...
;             union PFU { u32x4 u; bf16x8 b; };
;             PFU p0, p1, p2, p3;
;             AT_EXP(s0, 0, p0);
; #pragma unroll
;             for (int kk = 0; kk < 2; ++kk)
; #pragma unroll
;                 for (int db = 0; db < NDB; ++db) vc[kk * NDB + db] = *(const ALAS bf16x8*)(sb + vx[kk + 2] + db * 4096);
;             __builtin_amdgcn_sched_barrier(0);
; #pragma unroll
;             for (int db = 0; db < NDB; ++db) o[db] = __builtin_amdgcn_mfma_f32_32x32x16_bf16(va[db], p0.b, o[db], 0, 0, 0);
;             AT_EXP(s0, 8, p1);
;             __builtin_amdgcn_sched_barrier(0);
; #pragma unroll
;             for (int db = 0; db < NDB; ++db) o[db] = __builtin_amdgcn_mfma_f32_32x32x16_bf16(va[NDB + db], p1.b, o[db], 0, 0, 0);
;             AT_EXP(s1, 0, p2);
;             __builtin_amdgcn_sched_barrier(0);
; #pragma unroll
;             for (int db = 0; db < NDB; ++db) o[db] = __builtin_amdgcn_mfma_f32_32x32x16_bf16(vc[db], p2.b, o[db], 0, 0, 0);
;             AT_EXP(s1, 8, p3);
;             __builtin_amdgcn_sched_barrier(0);
; #pragma unroll
;             for (int db = 0; db < NDB; ++db) o[db] = __builtin_amdgcn_mfma_f32_32x32x16_bf16(vc[NDB + db], p3.b, o[db], 0, 0, 0);
;             __builtin_amdgcn_sched_barrier(0);
;     ...
;             l_run += ls0 + ls1;
.LSPs_pv:
	s_cmp_eq_u32 s79, 0
	s_cbranch_scc1 .LSPs_pure
	s_waitcnt lgkmcnt(4)
	v_mfma_f32_32x32x16_bf16 v[50:65], v[146:149], v[238:241], v[50:65]
	v_exp_f32_e32 v98, v98
	v_exp_f32_e32 v99, v99
	v_mfma_f32_32x32x16_bf16 v[34:49], v[150:153], v[238:241], v[34:49]
	v_exp_f32_e32 v100, v100
	v_exp_f32_e32 v101, v101
	v_mfma_f32_32x32x16_bf16 v[18:33], v[154:157], v[238:241], v[18:33]
	v_exp_f32_e32 v102, v102
	v_exp_f32_e32 v103, v103
	v_add_f32_e32 v228, v98, v100
	v_add_f32_e32 v229, v99, v101
	v_mfma_f32_32x32x16_bf16 v[2:17], v[158:161], v[238:241], v[2:17]
	v_exp_f32_e32 v104, v104
	v_exp_f32_e32 v105, v105
	v_add_f32_e32 v228, v228, v102
	v_add_f32_e32 v229, v229, v103
	v_add3_u32 v236, s99, v183, v187
	ds_read_b128 v[146:149], v236 offset:16384
	ds_read_b128 v[150:153], v236 offset:20480
	ds_read_b128 v[154:157], v236 offset:24576
	ds_read_b128 v[158:161], v236 offset:28672
	s_waitcnt lgkmcnt(4)
	v_mfma_f32_32x32x16_bf16 v[50:65], v[130:133], v[242:245], v[50:65]
	v_exp_f32_e32 v106, v106
	v_exp_f32_e32 v107, v107
	v_add_f32_e32 v228, v228, v104
	v_add_f32_e32 v229, v229, v105
	v_cvt_pk_bf16_f32 v238, v98, v99
	v_mfma_f32_32x32x16_bf16 v[34:49], v[134:137], v[242:245], v[34:49]
	v_exp_f32_e32 v108, v108
	v_exp_f32_e32 v109, v109
	v_add_f32_e32 v228, v228, v106
	v_add_f32_e32 v229, v229, v107
	v_cvt_pk_bf16_f32 v239, v100, v101
	v_mfma_f32_32x32x16_bf16 v[18:33], v[138:141], v[242:245], v[18:33]
	v_exp_f32_e32 v110, v110
	v_exp_f32_e32 v111, v111
	v_add_f32_e32 v228, v228, v108
	v_add_f32_e32 v229, v229, v109
	v_cvt_pk_bf16_f32 v240, v102, v103
	v_mfma_f32_32x32x16_bf16 v[2:17], v[142:145], v[242:245], v[2:17]
	v_exp_f32_e32 v112, v112
	v_exp_f32_e32 v113, v113
	v_add_f32_e32 v228, v228, v110
	v_add_f32_e32 v229, v229, v111
	v_cvt_pk_bf16_f32 v241, v104, v105
	v_add3_u32 v237, s99, v190, v187
	ds_read_b128 v[130:133], v237 offset:16384
	ds_read_b128 v[134:137], v237 offset:20480
	ds_read_b128 v[138:141], v237 offset:24576
	ds_read_b128 v[142:145], v237 offset:28672
	s_waitcnt lgkmcnt(4)
	v_mfma_f32_32x32x16_bf16 v[50:65], v[146:149], v[246:249], v[50:65]
	v_exp_f32_e32 v82, v82
	v_exp_f32_e32 v83, v83
	v_add_f32_e32 v228, v228, v112
	v_add_f32_e32 v229, v229, v113
	v_cvt_pk_bf16_f32 v242, v106, v107
	v_lshl_add_u64 v[174:175], v[174:175], 0, s[60:61]
	v_lshl_add_u64 v[172:173], v[172:173], 0, s[48:49]
	v_mfma_f32_32x32x16_bf16 v[34:49], v[150:153], v[246:249], v[34:49]
	v_exp_f32_e32 v84, v84
	v_exp_f32_e32 v85, v85
	v_add_f32_e32 v228, v228, v82
	v_add_f32_e32 v229, v229, v83
	v_cvt_pk_bf16_f32 v243, v108, v109
	s_add_i32 s98, s78, 0x10000
	s_and_b32 s98, s98, 0x18000
	v_mfma_f32_32x32x16_bf16 v[18:33], v[154:157], v[246:249], v[18:33]
	v_exp_f32_e32 v86, v86
	v_exp_f32_e32 v87, v87
	v_add_f32_e32 v228, v228, v84
	v_add_f32_e32 v229, v229, v85
	v_cvt_pk_bf16_f32 v244, v110, v111
	s_add_i32 s98, s98, s29
	s_add_i32 s101, s78, 0x8000
	v_mfma_f32_32x32x16_bf16 v[2:17], v[158:161], v[246:249], v[2:17]
	v_exp_f32_e32 v88, v88
	v_exp_f32_e32 v89, v89
	v_add_f32_e32 v228, v228, v86
	v_add_f32_e32 v229, v229, v87
	v_cvt_pk_bf16_f32 v245, v112, v113
	s_and_b32 s101, s101, 0x18000
	s_add_i32 s101, s101, s29
	s_waitcnt lgkmcnt(0)
	v_mfma_f32_32x32x16_bf16 v[50:65], v[130:133], v[250:253], v[50:65]
	v_exp_f32_e32 v90, v90
	v_exp_f32_e32 v91, v91
	v_add_f32_e32 v228, v228, v88
	v_add_f32_e32 v229, v229, v89
	v_cvt_pk_bf16_f32 v246, v82, v83
	s_add_i32 s80, s78, 0xffff8000
	s_and_b32 s80, s80, 0x18000
	v_mfma_f32_32x32x16_bf16 v[34:49], v[134:137], v[250:253], v[34:49]
	v_exp_f32_e32 v92, v92
	v_exp_f32_e32 v93, v93
	v_add_f32_e32 v228, v228, v90
	v_add_f32_e32 v229, v229, v91
	v_cvt_pk_bf16_f32 v247, v84, v85
	s_add_i32 s99, s78, 0xffff0000
	s_and_b32 s99, s99, 0x18000
	v_mfma_f32_32x32x16_bf16 v[18:33], v[138:141], v[250:253], v[18:33]
	v_exp_f32_e32 v94, v94
	v_exp_f32_e32 v95, v95
	v_add_f32_e32 v228, v228, v92
	v_add_f32_e32 v229, v229, v93
	v_cvt_pk_bf16_f32 v248, v86, v87
	v_lshl_add_u64 v[208:209], v[174:175], 0, s[40:41]
	v_lshl_add_u64 v[210:211], v[172:173], 0, s[40:41]
	v_mfma_f32_32x32x16_bf16 v[2:17], v[142:145], v[250:253], v[2:17]
	v_exp_f32_e32 v96, v96
	v_exp_f32_e32 v97, v97
	v_add_f32_e32 v228, v228, v94
	v_add_f32_e32 v229, v229, v95
	v_cvt_pk_bf16_f32 v249, v88, v89
	v_add3_u32 v212, s80, v178, v162
	v_add3_u32 v213, s80, v180, v162
	v_add3_u32 v214, s80, v182, v162
	v_add_f32_e32 v228, v228, v96
	v_add_f32_e32 v229, v229, v97
	v_cvt_pk_bf16_f32 v250, v90, v91
	v_cvt_pk_bf16_f32 v251, v92, v93
	v_cvt_pk_bf16_f32 v252, v94, v95
	v_cvt_pk_bf16_f32 v253, v96, v97
	v_add3_u32 v215, s80, v184, v162
	v_add_f32_e32 v228, v228, v229
	v_cmp_nge_f32_e32 vcc, 0x53800000, v228
	s_cbranch_vccnz .LSPs_redo
	s_add_i32 s79, s79, 1
	s_add_i32 s78, s78, 0x8000
	s_addk_i32 s77, 0x100
	s_add_i32 s76, s76, 64
	v_add_f32_e32 v0, v0, v228
	s_cmpk_eq_i32 s77, 0x2000
	s_cbranch_scc0 .LSPs_top
	s_branch .LSPs_exit
; template <bool WIN> ...
;     ...
;             {
;                 bf16x8 ka[8];
; #pragma unroll
;                 for (int ds = 0; ds < 4; ++ds) { ka[2 * ds] = *(const ALAS bf16x8*)(sb + kx[ds]); ka[2 * ds + 1] = *(const ALAS bf16x8*)(sb + kx[ds] + 4096); }
;                 __builtin_amdgcn_sched_barrier(0);
;                 s0 = __builtin_amdgcn_mfma_f32_32x32x16_bf16(ka[0], qf(0), cvec, 0, 0, 0);
;                 s1 = __builtin_amdgcn_mfma_f32_32x32x16_bf16(ka[1], qf(0), cvec, 0, 0, 0);
; #pragma unroll
;                 for (int ds = 1; ds < 4; ++ds) {
;                     s0 = __builtin_amdgcn_mfma_f32_32x32x16_bf16(ka[2 * ds], qf(ds), s0, 0, 0, 0);
;                     s1 = __builtin_amdgcn_mfma_f32_32x32x16_bf16(ka[2 * ds + 1], qf(ds), s1, 0, 0, 0);
;                 }
;             }
;             bf16x8 va[2 * NDB], vc[2 * NDB];
; #pragma unroll
;             for (int kk = 0; kk < 2; ++kk)
; #pragma unroll
;                 for (int db = 0; db < NDB; ++db) va[kk * NDB + db] = *(const ALAS bf16x8*)(sb + vx[kk] + db * 4096);
;     ...
;             float ls0 = 0.f, ls1 = 0.f;
;     ...
;             union PFU { u32x4 u; bf16x8 b; };
;             PFU p0, p1, p2, p3;
;             AT_EXP(s0, 0, p0);
; #pragma unroll
;             for (int kk = 0; kk < 2; ++kk)
; #pragma unroll
;                 for (int db = 0; db < NDB; ++db) vc[kk * NDB + db] = *(const ALAS bf16x8*)(sb + vx[kk + 2] + db * 4096);
;             __builtin_amdgcn_sched_barrier(0);
; #pragma unroll
;             for (int db = 0; db < NDB; ++db) o[db] = __builtin_amdgcn_mfma_f32_32x32x16_bf16(va[db], p0.b, o[db], 0, 0, 0);
;             AT_EXP(s0, 8, p1);
;             __builtin_amdgcn_sched_barrier(0);
; #pragma unroll
;             for (int db = 0; db < NDB; ++db) o[db] = __builtin_amdgcn_mfma_f32_32x32x16_bf16(va[NDB + db], p1.b, o[db], 0, 0, 0);
;             AT_EXP(s1, 0, p2);
;             __builtin_amdgcn_sched_barrier(0);
; #pragma unroll
;             for (int db = 0; db < NDB; ++db) o[db] = __builtin_amdgcn_mfma_f32_32x32x16_bf16(vc[db], p2.b, o[db], 0, 0, 0);
;             AT_EXP(s1, 8, p3);
;             __builtin_amdgcn_sched_barrier(0);
; #pragma unroll
;             for (int db = 0; db < NDB; ++db) o[db] = __builtin_amdgcn_mfma_f32_32x32x16_bf16(vc[NDB + db], p3.b, o[db], 0, 0, 0);
;             __builtin_amdgcn_sched_barrier(0);
;     ...
;             l_run += ls0 + ls1;
.LSPs_pure:
	v_lshl_add_u64 v[174:175], v[174:175], 0, s[60:61]
	v_lshl_add_u64 v[172:173], v[172:173], 0, s[48:49]
	s_add_i32 s98, s78, 0x10000
	s_and_b32 s98, s98, 0x18000
	s_add_i32 s98, s98, s29
	s_add_i32 s101, s78, 0x8000
	s_and_b32 s101, s101, 0x18000
	s_add_i32 s101, s101, s29
	s_add_i32 s80, s78, 0xffff8000
	s_and_b32 s80, s80, 0x18000
	s_add_i32 s99, s78, 0xffff0000
	s_and_b32 s99, s99, 0x18000
	v_lshl_add_u64 v[208:209], v[174:175], 0, s[40:41]
	v_lshl_add_u64 v[210:211], v[172:173], 0, s[40:41]
	v_add3_u32 v212, s80, v178, v162
	v_add3_u32 v213, s80, v180, v162
	v_add3_u32 v214, s80, v182, v162
	v_add3_u32 v215, s80, v184, v162
	v_exp_f32_e32 v98, v98
	v_exp_f32_e32 v99, v99
	v_exp_f32_e32 v100, v100
	v_exp_f32_e32 v101, v101
	v_exp_f32_e32 v102, v102
	v_exp_f32_e32 v103, v103
	v_exp_f32_e32 v104, v104
	v_exp_f32_e32 v105, v105
	v_cvt_pk_bf16_f32 v238, v98, v99
	v_cvt_pk_bf16_f32 v239, v100, v101
	v_cvt_pk_bf16_f32 v240, v102, v103
	v_cvt_pk_bf16_f32 v241, v104, v105
	v_mov_b32_e32 v228, v98
	v_mov_b32_e32 v229, v102
	v_add_f32_e32 v228, v228, v99
	v_add_f32_e32 v229, v229, v103
	v_add_f32_e32 v228, v228, v100
	v_add_f32_e32 v229, v229, v104
	v_add_f32_e32 v228, v228, v101
	v_add_f32_e32 v229, v229, v105
	v_exp_f32_e32 v106, v106
	v_exp_f32_e32 v107, v107
	v_exp_f32_e32 v108, v108
	v_exp_f32_e32 v109, v109
	v_exp_f32_e32 v110, v110
	v_exp_f32_e32 v111, v111
	v_exp_f32_e32 v112, v112
	v_exp_f32_e32 v113, v113
	v_cvt_pk_bf16_f32 v242, v106, v107
	v_cvt_pk_bf16_f32 v243, v108, v109
	v_cvt_pk_bf16_f32 v244, v110, v111
	v_cvt_pk_bf16_f32 v245, v112, v113
	v_add_f32_e32 v228, v228, v106
	v_add_f32_e32 v229, v229, v110
	v_add_f32_e32 v228, v228, v107
	v_add_f32_e32 v229, v229, v111
	v_add_f32_e32 v228, v228, v108
	v_add_f32_e32 v229, v229, v112
	v_add_f32_e32 v228, v228, v109
	v_add_f32_e32 v229, v229, v113
	v_exp_f32_e32 v82, v82
	v_exp_f32_e32 v83, v83
	v_exp_f32_e32 v84, v84
	v_exp_f32_e32 v85, v85
	v_exp_f32_e32 v86, v86
	v_exp_f32_e32 v87, v87
	v_exp_f32_e32 v88, v88
	v_exp_f32_e32 v89, v89
	v_cvt_pk_bf16_f32 v246, v82, v83
	v_cvt_pk_bf16_f32 v247, v84, v85
	v_cvt_pk_bf16_f32 v248, v86, v87
	v_cvt_pk_bf16_f32 v249, v88, v89
	v_add_f32_e32 v228, v228, v82
	v_add_f32_e32 v229, v229, v86
	v_add_f32_e32 v228, v228, v83
	v_add_f32_e32 v229, v229, v87
	v_add_f32_e32 v228, v228, v84
	v_add_f32_e32 v229, v229, v88
	v_add_f32_e32 v228, v228, v85
	v_add_f32_e32 v229, v229, v89
	v_exp_f32_e32 v90, v90
	v_exp_f32_e32 v91, v91
	v_exp_f32_e32 v92, v92
	v_exp_f32_e32 v93, v93
	v_exp_f32_e32 v94, v94
	v_exp_f32_e32 v95, v95
	v_exp_f32_e32 v96, v96
	v_exp_f32_e32 v97, v97
	v_cvt_pk_bf16_f32 v250, v90, v91
	v_cvt_pk_bf16_f32 v251, v92, v93
	v_cvt_pk_bf16_f32 v252, v94, v95
	v_cvt_pk_bf16_f32 v253, v96, v97
	v_add_f32_e32 v228, v228, v90
	v_add_f32_e32 v229, v229, v94
	v_add_f32_e32 v228, v228, v91
	v_add_f32_e32 v229, v229, v95
	v_add_f32_e32 v228, v228, v92
	v_add_f32_e32 v229, v229, v96
	v_add_f32_e32 v228, v228, v93
	v_add_f32_e32 v229, v229, v97
	v_add_f32_e32 v228, v228, v229
	v_cmp_nge_f32_e32 vcc, 0x53800000, v228
	s_cbranch_vccnz .LSPs_redo
	s_add_i32 s79, s79, 1
	s_add_i32 s78, s78, 0x8000
	s_addk_i32 s77, 0x100
	s_add_i32 s76, s76, 64
	v_add_f32_e32 v0, v0, v228
	s_cmpk_eq_i32 s77, 0x2000
	s_cbranch_scc0 .LSPs_top
	s_branch .LSPs_exit
.LSPs_redo:
	s_add_i32 s80, s80, 0x18000
	s_and_b32 s80, s80, 0x18000
	v_add3_u32 v203, s80, v178, v162
	ds_read_b128 v[130:133], v203
	ds_read_b128 v[134:137], v203 offset:4096
	v_add3_u32 v203, s80, v180, v162
	ds_read_b128 v[138:141], v203
	ds_read_b128 v[142:145], v203 offset:4096
	v_add3_u32 v203, s80, v182, v162
	ds_read_b128 v[146:149], v203
	ds_read_b128 v[150:153], v203 offset:4096
	v_add3_u32 v203, s80, v184, v162
	ds_read_b128 v[158:161], v203
	ds_read_b128 v[204:207], v203 offset:4096
	s_waitcnt lgkmcnt(0)
	v_mfma_f32_32x32x16_bf16 v[98:113], v[130:133], v[126:129], v[66:81]
	v_mfma_f32_32x32x16_bf16 v[82:97], v[134:137], v[126:129], v[66:81]
	v_mfma_f32_32x32x16_bf16 v[98:113], v[138:141], v[122:125], v[98:113]
	v_mfma_f32_32x32x16_bf16 v[82:97], v[142:145], v[122:125], v[82:97]
	v_mfma_f32_32x32x16_bf16 v[98:113], v[146:149], v[118:121], v[98:113]
	v_mfma_f32_32x32x16_bf16 v[82:97], v[150:153], v[118:121], v[82:97]
	v_mfma_f32_32x32x16_bf16 v[98:113], v[158:161], v[114:117], v[98:113]
	v_mfma_f32_32x32x16_bf16 v[82:97], v[204:207], v[114:117], v[82:97]
	s_nop 7
	s_nop 7
	s_andn2_b64 vcc, exec, s[64:65]
	s_cbranch_vccnz .LSPs_redomax
	v_add_u32_e32 v203, s77, v171
	v_add_u32_e32 v204, 0x23b80, v203
	v_add_u32_e32 v206, 0x23c00, v203
	v_add_u32_e32 v210, 0x23c08, v203
	v_add_u32_e32 v208, 0x23b88, v203
	v_add_u32_e32 v218, 0x23c10, v203
	v_add_u32_e32 v212, 0x23b90, v203
	v_add_u32_e32 v216, 0x23c18, v203
	v_add_u32_e32 v214, 0x23b98, v203
	ds_read2_b32 v[204:205], v204 offset1:1
	ds_read2_b32 v[206:207], v206 offset1:1
	ds_read2_b32 v[208:209], v208 offset1:1
	ds_read2_b32 v[210:211], v210 offset1:1
	ds_read2_b32 v[212:213], v212 offset1:1
	ds_read2_b32 v[214:215], v214 offset1:1
	ds_read2_b32 v[216:217], v216 offset1:1
	ds_read2_b32 v[218:219], v218 offset1:1
	v_add_u32_e32 v220, 0x23bc0, v203
	v_add_u32_e32 v222, 0x23c40, v203
	v_add_u32_e32 v226, 0x23c48, v203
	v_add_u32_e32 v224, 0x23bc8, v203
	v_add_u32_e32 v228, 0x23bd0, v203
	v_add_u32_e32 v234, 0x23c58, v203
	ds_read2_b32 v[220:221], v220 offset1:1
	ds_read2_b32 v[222:223], v222 offset1:1
	ds_read2_b32 v[224:225], v224 offset1:1
	ds_read2_b32 v[226:227], v226 offset1:1
	v_add_u32_e32 v231, 0x23c50, v203
	v_add_u32_e32 v203, 0x23bd8, v203
	ds_read2_b32 v[228:229], v228 offset1:1
	ds_read2_b32 v[232:233], v203 offset1:1
	ds_read2_b32 v[234:235], v234 offset1:1
	ds_read2_b32 v[236:237], v231 offset1:1
	s_waitcnt lgkmcnt(10)
	v_pk_add_f32 v[104:105], v[104:105], v[214:215]
	v_pk_add_f32 v[102:103], v[102:103], v[212:213]
	v_pk_add_f32 v[100:101], v[100:101], v[208:209]
	s_waitcnt lgkmcnt(2)
	v_pk_add_f32 v[112:113], v[112:113], v[232:233]
	v_pk_add_f32 v[110:111], v[110:111], v[228:229]
	v_pk_add_f32 v[108:109], v[108:109], v[224:225]
	v_pk_add_f32 v[106:107], v[106:107], v[220:221]
	v_pk_add_f32 v[98:99], v[98:99], v[204:205]
	v_pk_add_f32 v[88:89], v[88:89], v[216:217]
	v_pk_add_f32 v[86:87], v[86:87], v[218:219]
	v_pk_add_f32 v[84:85], v[84:85], v[210:211]
	s_waitcnt lgkmcnt(1)
	v_pk_add_f32 v[96:97], v[96:97], v[234:235]
	s_waitcnt lgkmcnt(0)
	v_pk_add_f32 v[94:95], v[94:95], v[236:237]
	v_pk_add_f32 v[92:93], v[92:93], v[226:227]
	v_pk_add_f32 v[90:91], v[90:91], v[222:223]
	v_pk_add_f32 v[82:83], v[82:83], v[206:207]

; #define ALAS __attribute__((address_space(3)))
; template <bool WIN> ...
;     ...
;             float ls0 = 0.f, ls1 = 0.f;
;     ...
;             union PFU { u32x4 u; bf16x8 b; };
;             PFU p0, p1, p2, p3;
;             AT_EXP(s0, 0, p0);
; #pragma unroll
;             for (int kk = 0; kk < 2; ++kk)
; #pragma unroll
;                 for (int db = 0; db < NDB; ++db) vc[kk * NDB + db] = *(const ALAS bf16x8*)(sb + vx[kk + 2] + db * 4096);
;             __builtin_amdgcn_sched_barrier(0);
; #pragma unroll
;             for (int db = 0; db < NDB; ++db) o[db] = __builtin_amdgcn_mfma_f32_32x32x16_bf16(va[db], p0.b, o[db], 0, 0, 0);
;             AT_EXP(s0, 8, p1);
;             __builtin_amdgcn_sched_barrier(0);
; #pragma unroll
;             for (int db = 0; db < NDB; ++db) o[db] = __builtin_amdgcn_mfma_f32_32x32x16_bf16(va[NDB + db], p1.b, o[db], 0, 0, 0);
;             AT_EXP(s1, 0, p2);
;             __builtin_amdgcn_sched_barrier(0);
; #pragma unroll
;             for (int db = 0; db < NDB; ++db) o[db] = __builtin_amdgcn_mfma_f32_32x32x16_bf16(vc[db], p2.b, o[db], 0, 0, 0);
;             AT_EXP(s1, 8, p3);
;             __builtin_amdgcn_sched_barrier(0);
; #pragma unroll
;             for (int db = 0; db < NDB; ++db) o[db] = __builtin_amdgcn_mfma_f32_32x32x16_bf16(vc[NDB + db], p3.b, o[db], 0, 0, 0);
;             __builtin_amdgcn_sched_barrier(0);
;     ...
;             l_run += ls0 + ls1;
.LSPs_pure2:
	s_add_i32 s80, s80, 0x8000
	s_and_b32 s80, s80, 0x18000
	v_lshl_add_u64 v[208:209], v[174:175], 0, s[40:41]
	v_lshl_add_u64 v[210:211], v[172:173], 0, s[40:41]
	v_add3_u32 v212, s80, v178, v162
	v_add3_u32 v213, s80, v180, v162
	v_add3_u32 v214, s80, v182, v162
	v_add3_u32 v215, s80, v184, v162
	v_exp_f32_e32 v98, v98
	v_exp_f32_e32 v99, v99
	v_exp_f32_e32 v100, v100
	v_exp_f32_e32 v101, v101
	v_exp_f32_e32 v102, v102
	v_exp_f32_e32 v103, v103
	v_exp_f32_e32 v104, v104
	v_exp_f32_e32 v105, v105
	v_cvt_pk_bf16_f32 v238, v98, v99
	v_cvt_pk_bf16_f32 v239, v100, v101
	v_cvt_pk_bf16_f32 v240, v102, v103
	v_cvt_pk_bf16_f32 v241, v104, v105
	v_mov_b32_e32 v228, v98
	v_mov_b32_e32 v229, v102
	v_add_f32_e32 v228, v228, v99
	v_add_f32_e32 v229, v229, v103
	v_add_f32_e32 v228, v228, v100
	v_add_f32_e32 v229, v229, v104
	v_add_f32_e32 v228, v228, v101
	v_add_f32_e32 v229, v229, v105
	v_exp_f32_e32 v106, v106
	v_exp_f32_e32 v107, v107
	v_exp_f32_e32 v108, v108
	v_exp_f32_e32 v109, v109
	v_exp_f32_e32 v110, v110
	v_exp_f32_e32 v111, v111
	v_exp_f32_e32 v112, v112
	v_exp_f32_e32 v113, v113
	v_cvt_pk_bf16_f32 v242, v106, v107
	v_cvt_pk_bf16_f32 v243, v108, v109
	v_cvt_pk_bf16_f32 v244, v110, v111
	v_cvt_pk_bf16_f32 v245, v112, v113
	v_add_f32_e32 v228, v228, v106
	v_add_f32_e32 v229, v229, v110
	v_add_f32_e32 v228, v228, v107
	v_add_f32_e32 v229, v229, v111
	v_add_f32_e32 v228, v228, v108
	v_add_f32_e32 v229, v229, v112
	v_add_f32_e32 v228, v228, v109
	v_add_f32_e32 v229, v229, v113
	v_exp_f32_e32 v82, v82
	v_exp_f32_e32 v83, v83
	v_exp_f32_e32 v84, v84
	v_exp_f32_e32 v85, v85
	v_exp_f32_e32 v86, v86
	v_exp_f32_e32 v87, v87
	v_exp_f32_e32 v88, v88
	v_exp_f32_e32 v89, v89
	v_cvt_pk_bf16_f32 v246, v82, v83
	v_cvt_pk_bf16_f32 v247, v84, v85
	v_cvt_pk_bf16_f32 v248, v86, v87
	v_cvt_pk_bf16_f32 v249, v88, v89
	v_add_f32_e32 v228, v228, v82
	v_add_f32_e32 v229, v229, v86
	v_add_f32_e32 v228, v228, v83
	v_add_f32_e32 v229, v229, v87
	v_add_f32_e32 v228, v228, v84
	v_add_f32_e32 v229, v229, v88
	v_add_f32_e32 v228, v228, v85
	v_add_f32_e32 v229, v229, v89
	v_exp_f32_e32 v90, v90
	v_exp_f32_e32 v91, v91
	v_exp_f32_e32 v92, v92
	v_exp_f32_e32 v93, v93
	v_exp_f32_e32 v94, v94
	v_exp_f32_e32 v95, v95
	v_exp_f32_e32 v96, v96
	v_exp_f32_e32 v97, v97
	v_cvt_pk_bf16_f32 v250, v90, v91
	v_cvt_pk_bf16_f32 v251, v92, v93
	v_cvt_pk_bf16_f32 v252, v94, v95
	v_cvt_pk_bf16_f32 v253, v96, v97
	v_add_f32_e32 v228, v228, v90
	v_add_f32_e32 v229, v229, v94
	v_add_f32_e32 v228, v228, v91
	v_add_f32_e32 v229, v229, v95
	v_add_f32_e32 v228, v228, v92
	v_add_f32_e32 v229, v229, v96
	v_add_f32_e32 v228, v228, v93
	v_add_f32_e32 v229, v229, v97
	v_add_f32_e32 v228, v228, v229
	s_add_i32 s79, s79, 1
	s_add_i32 s78, s78, 0x8000
	s_addk_i32 s77, 0x100
	s_add_i32 s76, s76, 64
	v_add_f32_e32 v0, v0, v228
	s_cmpk_eq_i32 s77, 0x2000
	s_cbranch_scc0 .LSPs_top
	s_branch .LSPs_exit

; template <bool WIN> ...
;     ...
;             const float cinit = near ? 0.f : (k0 > qw ? cfar_hi : cfar_lo);
;             if (__builtin_expect(cinit != cbase, 0)) { cbase = cinit; asm volatile("" ::: "memory");
; #pragma unroll
;                 for (int r = 0; r < 16; ++r) cvec[r] = cbase - m_ref; }
.LSPs_cin:
	v_mov_b32_e32 v98, m0
	s_mov_b32 s100, m0
	v_sub_f32_e32 v82, v98, v201
	v_mov_b32_e32 v202, v98
	v_mov_b32_e32 v66, v82
	v_mov_b32_e32 v67, v82
	v_mov_b32_e32 v68, v82
	v_mov_b32_e32 v69, v82
	v_mov_b32_e32 v70, v82
	v_mov_b32_e32 v71, v82
	v_mov_b32_e32 v72, v82
	v_mov_b32_e32 v73, v82
	v_mov_b32_e32 v74, v82
	v_mov_b32_e32 v75, v82
	v_mov_b32_e32 v76, v82
	v_mov_b32_e32 v77, v82
	v_mov_b32_e32 v78, v82
	v_mov_b32_e32 v79, v82
	v_mov_b32_e32 v80, v82
	v_mov_b32_e32 v81, v82
	s_branch .LSPs_qk
